# v31 + saddr-form LDS-DMA (no 64-bit VALU address math) in the four big K-loops
# baseline (speedup 1.0000x reference)
.LBB0_132:
	v_add_u32_e32 v138, 0x10000, v141
	ds_read_b128 v[144:147], v138
	ds_read_b128 v[148:151], v138 offset:1024
	ds_read_b128 v[152:155], v138 offset:2048
	ds_read_b128 v[156:159], v138 offset:3072
	ds_read_b128 v[160:163], v142
	ds_read_b128 v[164:167], v142 offset:1024
	ds_read_b128 v[168:171], v142 offset:2048
	ds_read_b128 v[172:175], v142 offset:3072
	ds_read_b128 v[176:179], v142 offset:4096
	ds_read_b128 v[180:183], v142 offset:5120
	ds_read_b128 v[184:187], v142 offset:6144
	ds_read_b128 v[188:191], v142 offset:7168
	v_add_u32_e32 v138, 0x14000, v141
	ds_read_b128 v[194:197], v138
	ds_read_b128 v[198:201], v138 offset:1024
	ds_read_b128 v[202:205], v138 offset:2048
	ds_read_b128 v[206:209], v138 offset:3072
	s_add_i32 s71, s4, 2
	s_add_u32 s5, s2, 0xfff80080
	s_addc_u32 s9, s3, -1
	s_add_i32 s46, 0, 0x10000
	s_cmp_eq_u32 s64, s4
	s_cselect_b32 s4, s28, s67
	s_cselect_b32 s35, s13, s9
	s_cselect_b32 s34, s12, s5
	s_cselect_b32 s5, s29, s69
	s_add_i32 m0, s40, 0xc000
	s_nop 0
	global_load_lds_dwordx4 v134, s[2:3]
	s_add_i32 m0, s40, 0xe000
	s_nop 0
	global_load_lds_dwordx4 v136, s[2:3]
	s_waitcnt vmcnt(8)
	s_waitcnt lgkmcnt(0)
	s_barrier
	s_setprio 1
	v_mfma_f32_16x16x32_bf16 v[124:127], v[144:147], v[160:163], v[124:127]
	v_mfma_f32_16x16x32_bf16 v[120:123], v[152:155], v[160:163], v[120:123]
	v_mfma_f32_16x16x32_bf16 v[116:119], v[144:147], v[168:171], v[116:119]
	v_mfma_f32_16x16x32_bf16 v[108:111], v[152:155], v[168:171], v[108:111]
	v_mfma_f32_16x16x32_bf16 v[100:103], v[144:147], v[176:179], v[100:103]
	v_mfma_f32_16x16x32_bf16 v[92:95], v[152:155], v[176:179], v[92:95]
	v_mfma_f32_16x16x32_bf16 v[84:87], v[144:147], v[184:187], v[84:87]
	v_mfma_f32_16x16x32_bf16 v[76:79], v[152:155], v[184:187], v[76:79]
	v_mfma_f32_16x16x32_bf16 v[124:127], v[148:151], v[164:167], v[124:127]
	v_mfma_f32_16x16x32_bf16 v[120:123], v[156:159], v[164:167], v[120:123]
	v_mfma_f32_16x16x32_bf16 v[116:119], v[148:151], v[172:175], v[116:119]
	v_mfma_f32_16x16x32_bf16 v[108:111], v[156:159], v[172:175], v[108:111]
	v_mfma_f32_16x16x32_bf16 v[100:103], v[148:151], v[180:183], v[100:103]
	v_mfma_f32_16x16x32_bf16 v[92:95], v[156:159], v[180:183], v[92:95]
	v_mfma_f32_16x16x32_bf16 v[84:87], v[148:151], v[188:191], v[84:87]
	v_mfma_f32_16x16x32_bf16 v[76:79], v[156:159], v[188:191], v[76:79]
	v_mfma_f32_16x16x32_bf16 v[112:115], v[194:197], v[160:163], v[112:115]
	v_mfma_f32_16x16x32_bf16 v[104:107], v[202:205], v[160:163], v[104:107]
	v_mfma_f32_16x16x32_bf16 v[96:99], v[194:197], v[168:171], v[96:99]
	v_mfma_f32_16x16x32_bf16 v[88:91], v[202:205], v[168:171], v[88:91]
	v_mfma_f32_16x16x32_bf16 v[80:83], v[194:197], v[176:179], v[80:83]
	v_mfma_f32_16x16x32_bf16 v[72:75], v[202:205], v[176:179], v[72:75]
	v_mfma_f32_16x16x32_bf16 v[68:71], v[194:197], v[184:187], v[68:71]
	v_mfma_f32_16x16x32_bf16 v[64:67], v[202:205], v[184:187], v[64:67]
	v_mfma_f32_16x16x32_bf16 v[112:115], v[198:201], v[164:167], v[112:115]
	v_mfma_f32_16x16x32_bf16 v[104:107], v[206:209], v[164:167], v[104:107]
	v_mfma_f32_16x16x32_bf16 v[96:99], v[198:201], v[172:175], v[96:99]
	v_mfma_f32_16x16x32_bf16 v[88:91], v[206:209], v[172:175], v[88:91]
	v_mfma_f32_16x16x32_bf16 v[80:83], v[198:201], v[180:183], v[80:83]
	v_mfma_f32_16x16x32_bf16 v[72:75], v[206:209], v[180:183], v[72:75]
	v_mfma_f32_16x16x32_bf16 v[68:71], v[198:201], v[188:191], v[68:71]
	v_mfma_f32_16x16x32_bf16 v[64:67], v[206:209], v[188:191], v[64:67]
	s_setprio 0
	s_barrier
	ds_read_b128 v[160:163], v142 offset:16384
	ds_read_b128 v[164:167], v142 offset:17408
	ds_read_b128 v[168:171], v142 offset:18432
	ds_read_b128 v[172:175], v142 offset:19456
	ds_read_b128 v[176:179], v142 offset:20480
	ds_read_b128 v[180:183], v142 offset:21504
	ds_read_b128 v[184:187], v142 offset:22528
	ds_read_b128 v[188:191], v142 offset:23552
	s_add_i32 s9, 0, 0x14000
	s_add_i32 s46, s46, s39
	s_add_u32 vcc_lo, s4, 0x80
	s_addc_u32 vcc_hi, s5, 0
	s_mov_b32 m0, s46
	s_nop 0
	global_load_lds_dwordx4 v192, s[4:5]
	s_add_i32 m0, s46, 0x2000
	s_nop 0
	global_load_lds_dwordx4 v132, s[4:5]
	s_mov_b32 m0, s40
	s_add_u32 s98, s34, 0x80
	s_addc_u32 s99, s35, 0
	global_load_lds_dwordx4 v128, s[34:35]
	s_mov_b32 m0, s41
	s_nop 0
	global_load_lds_dwordx4 v130, s[34:35]
	s_add_u32 s46, s4, 0x80000
	s_addc_u32 s47, s5, 0
	s_add_i32 s9, s9, s39
	s_mov_b32 m0, s9
	s_nop 0
	global_load_lds_dwordx4 v192, s[46:47]
	s_add_i32 m0, s9, 0x2000
	s_nop 0
	global_load_lds_dwordx4 v132, s[46:47]
	s_waitcnt vmcnt(8)
	s_waitcnt lgkmcnt(0)
	s_barrier
	s_setprio 1
	v_mfma_f32_16x16x32_bf16 v[60:63], v[144:147], v[160:163], v[60:63]
	v_mfma_f32_16x16x32_bf16 v[56:59], v[152:155], v[160:163], v[56:59]
	v_mfma_f32_16x16x32_bf16 v[52:55], v[144:147], v[168:171], v[52:55]
	v_mfma_f32_16x16x32_bf16 v[44:47], v[152:155], v[168:171], v[44:47]
	v_mfma_f32_16x16x32_bf16 v[36:39], v[144:147], v[176:179], v[36:39]
	v_mfma_f32_16x16x32_bf16 v[28:31], v[152:155], v[176:179], v[28:31]
	v_mfma_f32_16x16x32_bf16 v[20:23], v[144:147], v[184:187], v[20:23]
	v_mfma_f32_16x16x32_bf16 v[12:15], v[152:155], v[184:187], v[12:15]
	v_mfma_f32_16x16x32_bf16 v[60:63], v[148:151], v[164:167], v[60:63]
	v_mfma_f32_16x16x32_bf16 v[56:59], v[156:159], v[164:167], v[56:59]
	v_mfma_f32_16x16x32_bf16 v[52:55], v[148:151], v[172:175], v[52:55]
	v_mfma_f32_16x16x32_bf16 v[44:47], v[156:159], v[172:175], v[44:47]
	v_mfma_f32_16x16x32_bf16 v[36:39], v[148:151], v[180:183], v[36:39]
	v_mfma_f32_16x16x32_bf16 v[28:31], v[156:159], v[180:183], v[28:31]
	v_mfma_f32_16x16x32_bf16 v[20:23], v[148:151], v[188:191], v[20:23]
	v_mfma_f32_16x16x32_bf16 v[12:15], v[156:159], v[188:191], v[12:15]
	v_mfma_f32_16x16x32_bf16 v[48:51], v[194:197], v[160:163], v[48:51]
	v_mfma_f32_16x16x32_bf16 v[40:43], v[202:205], v[160:163], v[40:43]
	v_mfma_f32_16x16x32_bf16 v[32:35], v[194:197], v[168:171], v[32:35]
	v_mfma_f32_16x16x32_bf16 v[24:27], v[202:205], v[168:171], v[24:27]
	v_mfma_f32_16x16x32_bf16 v[16:19], v[194:197], v[176:179], v[16:19]
	v_mfma_f32_16x16x32_bf16 v[8:11], v[202:205], v[176:179], v[8:11]
	v_mfma_f32_16x16x32_bf16 v[4:7], v[194:197], v[184:187], v[4:7]
	v_mfma_f32_16x16x32_bf16 v[0:3], v[202:205], v[184:187], v[0:3]
	v_mfma_f32_16x16x32_bf16 v[48:51], v[198:201], v[164:167], v[48:51]
	v_mfma_f32_16x16x32_bf16 v[40:43], v[206:209], v[164:167], v[40:43]
	v_mfma_f32_16x16x32_bf16 v[32:35], v[198:201], v[172:175], v[32:35]
	v_mfma_f32_16x16x32_bf16 v[24:27], v[206:209], v[172:175], v[24:27]
	v_mfma_f32_16x16x32_bf16 v[16:19], v[198:201], v[180:183], v[16:19]
	v_mfma_f32_16x16x32_bf16 v[8:11], v[206:209], v[180:183], v[8:11]
	v_mfma_f32_16x16x32_bf16 v[4:7], v[198:201], v[188:191], v[4:7]
	v_mfma_f32_16x16x32_bf16 v[0:3], v[206:209], v[188:191], v[0:3]
	s_setprio 0
	s_barrier
	v_add_u32_e32 v143, 0x18000, v141
	ds_read_b128 v[144:147], v143
	ds_read_b128 v[148:151], v143 offset:1024
	ds_read_b128 v[152:155], v143 offset:2048
	ds_read_b128 v[156:159], v143 offset:3072
	ds_read_b128 v[160:163], v142 offset:32768
	ds_read_b128 v[164:167], v142 offset:33792
	ds_read_b128 v[168:171], v142 offset:34816
	ds_read_b128 v[172:175], v142 offset:35840
	ds_read_b128 v[176:179], v142 offset:36864
	ds_read_b128 v[180:183], v142 offset:37888
	ds_read_b128 v[184:187], v142 offset:38912
	ds_read_b128 v[188:191], v142 offset:39936
	v_add_u32_e32 v143, 0x1c000, v141
	ds_read_b128 v[194:197], v143
	ds_read_b128 v[198:201], v143 offset:1024
	ds_read_b128 v[202:205], v143 offset:2048
	ds_read_b128 v[206:209], v143 offset:3072
	s_add_i32 s9, 0, 0x18000
	s_add_u32 s34, s34, 0x80000
	s_addc_u32 s35, s35, 0
	s_mov_b32 m0, s48
	s_nop 0
	global_load_lds_dwordx4 v128, s[34:35]
	s_mov_b32 m0, s49
	s_nop 0
	global_load_lds_dwordx4 v130, s[34:35]
	s_waitcnt vmcnt(8)
	s_waitcnt lgkmcnt(0)
	s_barrier
	s_setprio 1
	v_mfma_f32_16x16x32_bf16 v[124:127], v[144:147], v[160:163], v[124:127]
	v_mfma_f32_16x16x32_bf16 v[120:123], v[152:155], v[160:163], v[120:123]
	v_mfma_f32_16x16x32_bf16 v[116:119], v[144:147], v[168:171], v[116:119]
	v_mfma_f32_16x16x32_bf16 v[108:111], v[152:155], v[168:171], v[108:111]
	v_mfma_f32_16x16x32_bf16 v[100:103], v[144:147], v[176:179], v[100:103]
	v_mfma_f32_16x16x32_bf16 v[92:95], v[152:155], v[176:179], v[92:95]
	v_mfma_f32_16x16x32_bf16 v[84:87], v[144:147], v[184:187], v[84:87]
	v_mfma_f32_16x16x32_bf16 v[76:79], v[152:155], v[184:187], v[76:79]
	v_mfma_f32_16x16x32_bf16 v[124:127], v[148:151], v[164:167], v[124:127]
	v_mfma_f32_16x16x32_bf16 v[120:123], v[156:159], v[164:167], v[120:123]
	v_mfma_f32_16x16x32_bf16 v[116:119], v[148:151], v[172:175], v[116:119]
	v_mfma_f32_16x16x32_bf16 v[108:111], v[156:159], v[172:175], v[108:111]
	v_mfma_f32_16x16x32_bf16 v[100:103], v[148:151], v[180:183], v[100:103]
	v_mfma_f32_16x16x32_bf16 v[92:95], v[156:159], v[180:183], v[92:95]
	v_mfma_f32_16x16x32_bf16 v[84:87], v[148:151], v[188:191], v[84:87]
	v_mfma_f32_16x16x32_bf16 v[76:79], v[156:159], v[188:191], v[76:79]
	v_mfma_f32_16x16x32_bf16 v[112:115], v[194:197], v[160:163], v[112:115]
	v_mfma_f32_16x16x32_bf16 v[104:107], v[202:205], v[160:163], v[104:107]
	v_mfma_f32_16x16x32_bf16 v[96:99], v[194:197], v[168:171], v[96:99]
	v_mfma_f32_16x16x32_bf16 v[88:91], v[202:205], v[168:171], v[88:91]
	v_mfma_f32_16x16x32_bf16 v[80:83], v[194:197], v[176:179], v[80:83]
	v_mfma_f32_16x16x32_bf16 v[72:75], v[202:205], v[176:179], v[72:75]
	v_mfma_f32_16x16x32_bf16 v[68:71], v[194:197], v[184:187], v[68:71]
	v_mfma_f32_16x16x32_bf16 v[64:67], v[202:205], v[184:187], v[64:67]
	v_mfma_f32_16x16x32_bf16 v[112:115], v[198:201], v[164:167], v[112:115]
	v_mfma_f32_16x16x32_bf16 v[104:107], v[206:209], v[164:167], v[104:107]
	v_mfma_f32_16x16x32_bf16 v[96:99], v[198:201], v[172:175], v[96:99]
	v_mfma_f32_16x16x32_bf16 v[88:91], v[206:209], v[172:175], v[88:91]
	v_mfma_f32_16x16x32_bf16 v[80:83], v[198:201], v[180:183], v[80:83]
	v_mfma_f32_16x16x32_bf16 v[72:75], v[206:209], v[180:183], v[72:75]
	v_mfma_f32_16x16x32_bf16 v[68:71], v[198:201], v[188:191], v[68:71]
	v_mfma_f32_16x16x32_bf16 v[64:67], v[206:209], v[188:191], v[64:67]
	s_setprio 0
	s_barrier
	ds_read_b128 v[160:163], v142 offset:49152
	ds_read_b128 v[164:167], v142 offset:50176
	ds_read_b128 v[168:171], v142 offset:51200
	ds_read_b128 v[172:175], v142 offset:52224
	ds_read_b128 v[176:179], v142 offset:53248
	ds_read_b128 v[180:183], v142 offset:54272
	ds_read_b128 v[184:187], v142 offset:55296
	ds_read_b128 v[188:191], v142 offset:56320
	s_add_i32 s34, 0, 0x1c000
	s_add_i32 s9, s9, s39
	s_mov_b32 m0, s9
	s_nop 0
	global_load_lds_dwordx4 v192, vcc
	s_add_i32 m0, s9, 0x2000
	s_nop 0
	global_load_lds_dwordx4 v132, vcc
	s_mov_b32 m0, s50
	s_nop 0
	global_load_lds_dwordx4 v128, s[98:99]
	s_mov_b32 m0, s51
	s_nop 0
	global_load_lds_dwordx4 v130, s[98:99]
	s_add_u32 s4, s4, 0x80080
	s_addc_u32 s5, s5, 0
	s_add_i32 s9, s34, s39
	s_mov_b32 m0, s9
	s_nop 0
	global_load_lds_dwordx4 v192, s[4:5]
	s_add_i32 m0, s9, 0x2000
	s_nop 0
	global_load_lds_dwordx4 v132, s[4:5]
	s_waitcnt vmcnt(8)
	s_waitcnt lgkmcnt(0)
	s_barrier
	s_setprio 1
	v_mfma_f32_16x16x32_bf16 v[60:63], v[144:147], v[160:163], v[60:63]
	v_mfma_f32_16x16x32_bf16 v[56:59], v[152:155], v[160:163], v[56:59]
	v_mfma_f32_16x16x32_bf16 v[52:55], v[144:147], v[168:171], v[52:55]
	v_mfma_f32_16x16x32_bf16 v[44:47], v[152:155], v[168:171], v[44:47]
	v_mfma_f32_16x16x32_bf16 v[36:39], v[144:147], v[176:179], v[36:39]
	v_mfma_f32_16x16x32_bf16 v[28:31], v[152:155], v[176:179], v[28:31]
	v_mfma_f32_16x16x32_bf16 v[20:23], v[144:147], v[184:187], v[20:23]
	v_mfma_f32_16x16x32_bf16 v[12:15], v[152:155], v[184:187], v[12:15]
	v_mfma_f32_16x16x32_bf16 v[60:63], v[148:151], v[164:167], v[60:63]
	v_mfma_f32_16x16x32_bf16 v[56:59], v[156:159], v[164:167], v[56:59]
	v_mfma_f32_16x16x32_bf16 v[52:55], v[148:151], v[172:175], v[52:55]
	v_mfma_f32_16x16x32_bf16 v[44:47], v[156:159], v[172:175], v[44:47]
	v_mfma_f32_16x16x32_bf16 v[36:39], v[148:151], v[180:183], v[36:39]
	v_mfma_f32_16x16x32_bf16 v[28:31], v[156:159], v[180:183], v[28:31]
	v_mfma_f32_16x16x32_bf16 v[20:23], v[148:151], v[188:191], v[20:23]
	v_mfma_f32_16x16x32_bf16 v[12:15], v[156:159], v[188:191], v[12:15]
	v_mfma_f32_16x16x32_bf16 v[48:51], v[194:197], v[160:163], v[48:51]
	v_mfma_f32_16x16x32_bf16 v[40:43], v[202:205], v[160:163], v[40:43]
	v_mfma_f32_16x16x32_bf16 v[32:35], v[194:197], v[168:171], v[32:35]
	v_mfma_f32_16x16x32_bf16 v[24:27], v[202:205], v[168:171], v[24:27]
	v_mfma_f32_16x16x32_bf16 v[16:19], v[194:197], v[176:179], v[16:19]
	v_mfma_f32_16x16x32_bf16 v[8:11], v[202:205], v[176:179], v[8:11]
	v_mfma_f32_16x16x32_bf16 v[4:7], v[194:197], v[184:187], v[4:7]
	v_mfma_f32_16x16x32_bf16 v[0:3], v[202:205], v[184:187], v[0:3]
	v_mfma_f32_16x16x32_bf16 v[48:51], v[198:201], v[164:167], v[48:51]
	v_mfma_f32_16x16x32_bf16 v[40:43], v[206:209], v[164:167], v[40:43]
	v_mfma_f32_16x16x32_bf16 v[32:35], v[198:201], v[172:175], v[32:35]
	v_mfma_f32_16x16x32_bf16 v[24:27], v[206:209], v[172:175], v[24:27]
	v_mfma_f32_16x16x32_bf16 v[16:19], v[198:201], v[180:183], v[16:19]
	v_mfma_f32_16x16x32_bf16 v[8:11], v[206:209], v[180:183], v[8:11]
	v_mfma_f32_16x16x32_bf16 v[4:7], v[198:201], v[188:191], v[4:7]
	v_mfma_f32_16x16x32_bf16 v[0:3], v[206:209], v[188:191], v[0:3]
	s_setprio 0
	s_add_u32 s2, s2, 0x100
	s_addc_u32 s3, s3, 0
	s_add_u32 s67, s67, 0x100
	s_addc_u32 s69, s69, 0
	s_cmp_ge_i32 s71, s63
	s_mov_b32 s4, s71
	s_barrier
	s_cbranch_scc0 .LBB0_132
	v_sub_co_u32_e64 v138, s[2:3], s66, 1
	s_nop 0
	v_readfirstlane_b32 s64, v138
	s_lshl_b64 s[4:5], s[64:65], 22
	v_readlane_b32 s34, v252, 9
	v_readlane_b32 s35, v252, 10
	s_add_u32 s4, s34, s4
	s_addc_u32 s5, s35, s5
	s_sub_i32 s9, s62, 32
	s_and_b64 s[2:3], s[2:3], exec
	v_readlane_b32 s34, v252, 7
	s_cselect_b32 s2, s62, s9
	v_readlane_b32 s35, v252, 8
	s_cselect_b32 s5, s35, s5
	s_cselect_b32 s4, s34, s4
	s_ashr_i32 s3, s2, 31
	s_lshl_b64 s[2:3], s[2:3], 20
	s_add_u32 s2, s4, s2
	v_mov_b32 v139, v140
	s_addc_u32 s3, s5, s3
	v_ashrrev_i32_e32 v138, 1, v139
	s_lshl_b32 s4, s58, 8
	v_and_b32_e32 v138, -8, v138
	s_or_b32 s4, s4, s53
	v_add_u32_e32 v138, s4, v138
	v_and_or_b32 v144, v139, 15, s52
	v_ashrrev_i32_e32 v139, 31, v138
	v_ashrrev_i32_e32 v145, 31, v144
	v_lshl_add_u64 v[146:147], v[138:139], 1, s[2:3]
	v_lshlrev_b64 v[138:139], 12, v[144:145]
	v_lshl_add_u64 v[138:139], v[146:147], 0, v[138:139]
	v_cvt_pk_bf16_f32 v124, v124, v125
	v_cvt_pk_bf16_f32 v125, v126, v127
	v_cvt_pk_bf16_f32 v126, v120, v121
	v_cvt_pk_bf16_f32 v127, v122, v123
	global_store_dwordx4 v[138:139], v[124:127], off
	v_cvt_pk_bf16_f32 v112, v112, v113
	v_cvt_pk_bf16_f32 v113, v114, v115
	v_cvt_pk_bf16_f32 v114, v104, v105
	v_or_b32_e32 v104, 16, v144
	v_ashrrev_i32_e32 v105, 31, v104
	v_lshlrev_b64 v[104:105], 12, v[104:105]
	v_cvt_pk_bf16_f32 v115, v106, v107
	global_store_dwordx4 v[138:139], v[112:115], off offset:256
	s_mov_b64 s[2:3], 0x80000
	s_mov_b32 s58, s55
	v_lshl_add_u64 v[112:113], v[146:147], 0, v[104:105]
	v_cvt_pk_bf16_f32 v104, v116, v117
	v_cvt_pk_bf16_f32 v105, v118, v119
	v_cvt_pk_bf16_f32 v106, v108, v109
	v_cvt_pk_bf16_f32 v107, v110, v111
	global_store_dwordx4 v[112:113], v[104:107], off
	v_cvt_pk_bf16_f32 v96, v96, v97
	v_cvt_pk_bf16_f32 v97, v98, v99
	v_cvt_pk_bf16_f32 v98, v88, v89
	v_or_b32_e32 v88, 32, v144
	v_ashrrev_i32_e32 v89, 31, v88
	v_lshlrev_b64 v[88:89], 12, v[88:89]
	v_cvt_pk_bf16_f32 v99, v90, v91
	global_store_dwordx4 v[112:113], v[96:99], off offset:256
	s_mov_b32 s62, s14
	s_mov_b32 s66, s15
	v_lshl_add_u64 v[96:97], v[146:147], 0, v[88:89]
	v_cvt_pk_bf16_f32 v88, v100, v101
	v_cvt_pk_bf16_f32 v89, v102, v103
	v_cvt_pk_bf16_f32 v90, v92, v93
	v_cvt_pk_bf16_f32 v91, v94, v95
	global_store_dwordx4 v[96:97], v[88:91], off
	v_cvt_pk_bf16_f32 v80, v80, v81
	v_cvt_pk_bf16_f32 v81, v82, v83
	v_cvt_pk_bf16_f32 v82, v72, v73
	v_or_b32_e32 v72, 48, v144
	v_ashrrev_i32_e32 v73, 31, v72
	v_lshlrev_b64 v[72:73], 12, v[72:73]
	v_cvt_pk_bf16_f32 v83, v74, v75
	global_store_dwordx4 v[96:97], v[80:83], off offset:256
	s_mov_b32 s63, s59
	s_mov_b64 s[4:5], s[28:29]
	v_lshl_add_u64 v[80:81], v[146:147], 0, v[72:73]
	v_cvt_pk_bf16_f32 v72, v84, v85
	v_cvt_pk_bf16_f32 v73, v86, v87
	v_cvt_pk_bf16_f32 v74, v76, v77
	v_cvt_pk_bf16_f32 v75, v78, v79
	global_store_dwordx4 v[80:81], v[72:75], off
	v_cvt_pk_bf16_f32 v68, v68, v69
	v_cvt_pk_bf16_f32 v69, v70, v71
	v_cvt_pk_bf16_f32 v70, v64, v65
	v_lshl_add_u64 v[64:65], v[138:139], 0, s[2:3]
	s_mov_b32 s2, 0x80000
	v_cvt_pk_bf16_f32 v71, v66, v67
	global_store_dwordx4 v[80:81], v[68:71], off offset:256
	v_cvt_pk_bf16_f32 v60, v60, v61
	v_cvt_pk_bf16_f32 v61, v62, v63
	v_cvt_pk_bf16_f32 v62, v56, v57
	v_add_co_u32_e32 v56, vcc, s2, v138
	v_cvt_pk_bf16_f32 v63, v58, v59
	s_mov_b64 s[2:3], 0x90000
	s_nop 0
	v_addc_co_u32_e32 v57, vcc, 0, v139, vcc
	global_store_dwordx4 v[56:57], v[60:63], off
	v_cvt_pk_bf16_f32 v48, v48, v49
	v_cvt_pk_bf16_f32 v49, v50, v51
	v_cvt_pk_bf16_f32 v50, v40, v41
	v_cvt_pk_bf16_f32 v51, v42, v43
	global_store_dwordx4 v[64:65], v[48:51], off offset:256
	v_cvt_pk_bf16_f32 v40, v52, v53
	v_cvt_pk_bf16_f32 v41, v54, v55
	v_cvt_pk_bf16_f32 v42, v44, v45
	v_cvt_pk_bf16_f32 v43, v46, v47
	s_nop 1
	v_lshl_add_u64 v[48:49], v[138:139], 0, s[2:3]
	s_mov_b32 s2, 0x90000
	v_add_co_u32_e32 v44, vcc, s2, v138
	s_mov_b64 s[2:3], 0xa0000
	s_nop 0
	v_addc_co_u32_e32 v45, vcc, 0, v139, vcc
	global_store_dwordx4 v[44:45], v[40:43], off
	v_cvt_pk_bf16_f32 v32, v32, v33
	v_cvt_pk_bf16_f32 v33, v34, v35
	v_cvt_pk_bf16_f32 v34, v24, v25
	v_cvt_pk_bf16_f32 v35, v26, v27
	global_store_dwordx4 v[48:49], v[32:35], off offset:256
	v_cvt_pk_bf16_f32 v24, v36, v37
	v_cvt_pk_bf16_f32 v25, v38, v39
	v_cvt_pk_bf16_f32 v26, v28, v29
	v_cvt_pk_bf16_f32 v27, v30, v31
	s_nop 1
	v_lshl_add_u64 v[32:33], v[138:139], 0, s[2:3]
	s_mov_b32 s2, 0xa0000
	v_add_co_u32_e32 v28, vcc, s2, v138
	s_mov_b64 s[2:3], 0xb0000
	s_nop 0
	v_addc_co_u32_e32 v29, vcc, 0, v139, vcc
	global_store_dwordx4 v[28:29], v[24:27], off
	v_cvt_pk_bf16_f32 v16, v16, v17
	v_cvt_pk_bf16_f32 v17, v18, v19
	v_cvt_pk_bf16_f32 v18, v8, v9
	v_cvt_pk_bf16_f32 v19, v10, v11
	global_store_dwordx4 v[32:33], v[16:19], off offset:256
	v_cvt_pk_bf16_f32 v8, v20, v21
	v_cvt_pk_bf16_f32 v9, v22, v23
	v_cvt_pk_bf16_f32 v10, v12, v13
	v_cvt_pk_bf16_f32 v11, v14, v15
	s_nop 1
	v_lshl_add_u64 v[16:17], v[138:139], 0, s[2:3]
	s_mov_b32 s2, 0xb0000
	v_add_co_u32_e32 v12, vcc, s2, v138
	s_mov_b64 s[2:3], s[12:13]
	s_nop 0
	v_addc_co_u32_e32 v13, vcc, 0, v139, vcc
	s_and_b64 vcc, exec, s[0:1]
	global_store_dwordx4 v[12:13], v[8:11], off
	v_cvt_pk_bf16_f32 v4, v4, v5
	v_cvt_pk_bf16_f32 v5, v6, v7
	v_cvt_pk_bf16_f32 v6, v0, v1
	v_cvt_pk_bf16_f32 v7, v2, v3
	global_store_dwordx4 v[16:17], v[4:7], off offset:256
	s_cbranch_vccz .LBB0_122
	s_waitcnt vmcnt(0)
	s_cmpk_gt_u32 s36, 0xff
	s_cbranch_scc1 .LBB0_136
	s_barrier

.LBB0_242:
	v_add_u32_e32 v138, 0x10000, v141
	ds_read_b128 v[144:147], v138
	ds_read_b128 v[148:151], v138 offset:1024
	ds_read_b128 v[152:155], v138 offset:2048
	ds_read_b128 v[156:159], v138 offset:3072
	ds_read_b128 v[160:163], v142
	ds_read_b128 v[164:167], v142 offset:1024
	ds_read_b128 v[168:171], v142 offset:2048
	ds_read_b128 v[172:175], v142 offset:3072
	ds_read_b128 v[176:179], v142 offset:4096
	ds_read_b128 v[180:183], v142 offset:5120
	ds_read_b128 v[184:187], v142 offset:6144
	ds_read_b128 v[188:191], v142 offset:7168
	v_add_u32_e32 v138, 0x14000, v141
	ds_read_b128 v[194:197], v138
	ds_read_b128 v[198:201], v138 offset:1024
	ds_read_b128 v[202:205], v138 offset:2048
	ds_read_b128 v[206:209], v138 offset:3072
	s_add_i32 s79, s4, 2
	s_add_u32 s5, s2, 0xffe00080
	s_addc_u32 s9, s3, -1
	s_add_i32 s46, 0, 0x10000
	s_cmp_eq_u32 s64, s4
	s_cselect_b32 s4, s36, s75
	s_cselect_b32 s39, s29, s9
	s_cselect_b32 s38, s28, s5
	s_cselect_b32 s5, s37, s78
	s_add_i32 m0, s50, 0xc000
	s_nop 0
	global_load_lds_dwordx4 v134, s[2:3]
	s_add_i32 m0, s50, 0xe000
	s_nop 0
	global_load_lds_dwordx4 v136, s[2:3]
	s_waitcnt vmcnt(8)
	s_waitcnt lgkmcnt(0)
	s_barrier
	s_setprio 1
	v_mfma_f32_16x16x32_bf16 v[124:127], v[144:147], v[160:163], v[124:127]
	v_mfma_f32_16x16x32_bf16 v[120:123], v[152:155], v[160:163], v[120:123]
	v_mfma_f32_16x16x32_bf16 v[116:119], v[144:147], v[168:171], v[116:119]
	v_mfma_f32_16x16x32_bf16 v[108:111], v[152:155], v[168:171], v[108:111]
	v_mfma_f32_16x16x32_bf16 v[100:103], v[144:147], v[176:179], v[100:103]
	v_mfma_f32_16x16x32_bf16 v[92:95], v[152:155], v[176:179], v[92:95]
	v_mfma_f32_16x16x32_bf16 v[84:87], v[144:147], v[184:187], v[84:87]
	v_mfma_f32_16x16x32_bf16 v[76:79], v[152:155], v[184:187], v[76:79]
	v_mfma_f32_16x16x32_bf16 v[124:127], v[148:151], v[164:167], v[124:127]
	v_mfma_f32_16x16x32_bf16 v[120:123], v[156:159], v[164:167], v[120:123]
	v_mfma_f32_16x16x32_bf16 v[116:119], v[148:151], v[172:175], v[116:119]
	v_mfma_f32_16x16x32_bf16 v[108:111], v[156:159], v[172:175], v[108:111]
	v_mfma_f32_16x16x32_bf16 v[100:103], v[148:151], v[180:183], v[100:103]
	v_mfma_f32_16x16x32_bf16 v[92:95], v[156:159], v[180:183], v[92:95]
	v_mfma_f32_16x16x32_bf16 v[84:87], v[148:151], v[188:191], v[84:87]
	v_mfma_f32_16x16x32_bf16 v[76:79], v[156:159], v[188:191], v[76:79]
	v_mfma_f32_16x16x32_bf16 v[112:115], v[194:197], v[160:163], v[112:115]
	v_mfma_f32_16x16x32_bf16 v[104:107], v[202:205], v[160:163], v[104:107]
	v_mfma_f32_16x16x32_bf16 v[96:99], v[194:197], v[168:171], v[96:99]
	v_mfma_f32_16x16x32_bf16 v[88:91], v[202:205], v[168:171], v[88:91]
	v_mfma_f32_16x16x32_bf16 v[80:83], v[194:197], v[176:179], v[80:83]
	v_mfma_f32_16x16x32_bf16 v[72:75], v[202:205], v[176:179], v[72:75]
	v_mfma_f32_16x16x32_bf16 v[68:71], v[194:197], v[184:187], v[68:71]
	v_mfma_f32_16x16x32_bf16 v[64:67], v[202:205], v[184:187], v[64:67]
	v_mfma_f32_16x16x32_bf16 v[112:115], v[198:201], v[164:167], v[112:115]
	v_mfma_f32_16x16x32_bf16 v[104:107], v[206:209], v[164:167], v[104:107]
	v_mfma_f32_16x16x32_bf16 v[96:99], v[198:201], v[172:175], v[96:99]
	v_mfma_f32_16x16x32_bf16 v[88:91], v[206:209], v[172:175], v[88:91]
	v_mfma_f32_16x16x32_bf16 v[80:83], v[198:201], v[180:183], v[80:83]
	v_mfma_f32_16x16x32_bf16 v[72:75], v[206:209], v[180:183], v[72:75]
	v_mfma_f32_16x16x32_bf16 v[68:71], v[198:201], v[188:191], v[68:71]
	v_mfma_f32_16x16x32_bf16 v[64:67], v[206:209], v[188:191], v[64:67]
	s_setprio 0
	s_barrier
	ds_read_b128 v[160:163], v142 offset:16384
	ds_read_b128 v[164:167], v142 offset:17408
	ds_read_b128 v[168:171], v142 offset:18432
	ds_read_b128 v[172:175], v142 offset:19456
	ds_read_b128 v[176:179], v142 offset:20480
	ds_read_b128 v[180:183], v142 offset:21504
	ds_read_b128 v[184:187], v142 offset:22528
	ds_read_b128 v[188:191], v142 offset:23552
	s_add_i32 s9, 0, 0x14000
	s_add_i32 s46, s46, s49
	s_add_u32 vcc_lo, s4, 0x80
	s_addc_u32 vcc_hi, s5, 0
	s_mov_b32 m0, s46
	s_nop 0
	global_load_lds_dwordx4 v192, s[4:5]
	s_add_i32 m0, s46, 0x2000
	s_nop 0
	global_load_lds_dwordx4 v132, s[4:5]
	s_mov_b32 m0, s50
	s_add_u32 s98, s38, 0x80
	s_addc_u32 s99, s39, 0
	global_load_lds_dwordx4 v128, s[38:39]
	s_mov_b32 m0, s51
	s_nop 0
	global_load_lds_dwordx4 v130, s[38:39]
	s_add_u32 s46, s4, 0x200000
	s_addc_u32 s47, s5, 0
	s_add_i32 s9, s9, s49
	s_mov_b32 m0, s9
	s_nop 0
	global_load_lds_dwordx4 v192, s[46:47]
	s_add_i32 m0, s9, 0x2000
	s_nop 0
	global_load_lds_dwordx4 v132, s[46:47]
	s_waitcnt vmcnt(8)
	s_waitcnt lgkmcnt(0)
	s_barrier
	s_setprio 1
	v_mfma_f32_16x16x32_bf16 v[60:63], v[144:147], v[160:163], v[60:63]
	v_mfma_f32_16x16x32_bf16 v[56:59], v[152:155], v[160:163], v[56:59]
	v_mfma_f32_16x16x32_bf16 v[52:55], v[144:147], v[168:171], v[52:55]
	v_mfma_f32_16x16x32_bf16 v[44:47], v[152:155], v[168:171], v[44:47]
	v_mfma_f32_16x16x32_bf16 v[36:39], v[144:147], v[176:179], v[36:39]
	v_mfma_f32_16x16x32_bf16 v[28:31], v[152:155], v[176:179], v[28:31]
	v_mfma_f32_16x16x32_bf16 v[20:23], v[144:147], v[184:187], v[20:23]
	v_mfma_f32_16x16x32_bf16 v[12:15], v[152:155], v[184:187], v[12:15]
	v_mfma_f32_16x16x32_bf16 v[60:63], v[148:151], v[164:167], v[60:63]
	v_mfma_f32_16x16x32_bf16 v[56:59], v[156:159], v[164:167], v[56:59]
	v_mfma_f32_16x16x32_bf16 v[52:55], v[148:151], v[172:175], v[52:55]
	v_mfma_f32_16x16x32_bf16 v[44:47], v[156:159], v[172:175], v[44:47]
	v_mfma_f32_16x16x32_bf16 v[36:39], v[148:151], v[180:183], v[36:39]
	v_mfma_f32_16x16x32_bf16 v[28:31], v[156:159], v[180:183], v[28:31]
	v_mfma_f32_16x16x32_bf16 v[20:23], v[148:151], v[188:191], v[20:23]
	v_mfma_f32_16x16x32_bf16 v[12:15], v[156:159], v[188:191], v[12:15]
	v_mfma_f32_16x16x32_bf16 v[48:51], v[194:197], v[160:163], v[48:51]
	v_mfma_f32_16x16x32_bf16 v[40:43], v[202:205], v[160:163], v[40:43]
	v_mfma_f32_16x16x32_bf16 v[32:35], v[194:197], v[168:171], v[32:35]
	v_mfma_f32_16x16x32_bf16 v[24:27], v[202:205], v[168:171], v[24:27]
	v_mfma_f32_16x16x32_bf16 v[16:19], v[194:197], v[176:179], v[16:19]
	v_mfma_f32_16x16x32_bf16 v[8:11], v[202:205], v[176:179], v[8:11]
	v_mfma_f32_16x16x32_bf16 v[4:7], v[194:197], v[184:187], v[4:7]
	v_mfma_f32_16x16x32_bf16 v[0:3], v[202:205], v[184:187], v[0:3]
	v_mfma_f32_16x16x32_bf16 v[48:51], v[198:201], v[164:167], v[48:51]
	v_mfma_f32_16x16x32_bf16 v[40:43], v[206:209], v[164:167], v[40:43]
	v_mfma_f32_16x16x32_bf16 v[32:35], v[198:201], v[172:175], v[32:35]
	v_mfma_f32_16x16x32_bf16 v[24:27], v[206:209], v[172:175], v[24:27]
	v_mfma_f32_16x16x32_bf16 v[16:19], v[198:201], v[180:183], v[16:19]
	v_mfma_f32_16x16x32_bf16 v[8:11], v[206:209], v[180:183], v[8:11]
	v_mfma_f32_16x16x32_bf16 v[4:7], v[198:201], v[188:191], v[4:7]
	v_mfma_f32_16x16x32_bf16 v[0:3], v[206:209], v[188:191], v[0:3]
	s_setprio 0
	s_barrier
	v_add_u32_e32 v143, 0x18000, v141
	ds_read_b128 v[144:147], v143
	ds_read_b128 v[148:151], v143 offset:1024
	ds_read_b128 v[152:155], v143 offset:2048
	ds_read_b128 v[156:159], v143 offset:3072
	ds_read_b128 v[160:163], v142 offset:32768
	ds_read_b128 v[164:167], v142 offset:33792
	ds_read_b128 v[168:171], v142 offset:34816
	ds_read_b128 v[172:175], v142 offset:35840
	ds_read_b128 v[176:179], v142 offset:36864
	ds_read_b128 v[180:183], v142 offset:37888
	ds_read_b128 v[184:187], v142 offset:38912
	ds_read_b128 v[188:191], v142 offset:39936
	v_add_u32_e32 v143, 0x1c000, v141
	ds_read_b128 v[194:197], v143
	ds_read_b128 v[198:201], v143 offset:1024
	ds_read_b128 v[202:205], v143 offset:2048
	ds_read_b128 v[206:209], v143 offset:3072
	s_add_i32 s9, 0, 0x18000
	s_add_u32 s38, s38, 0x200000
	s_addc_u32 s39, s39, 0
	s_mov_b32 m0, s52
	s_nop 0
	global_load_lds_dwordx4 v128, s[38:39]
	s_mov_b32 m0, s53
	s_nop 0
	global_load_lds_dwordx4 v130, s[38:39]
	s_waitcnt vmcnt(8)
	s_waitcnt lgkmcnt(0)
	s_barrier
	s_setprio 1
	v_mfma_f32_16x16x32_bf16 v[124:127], v[144:147], v[160:163], v[124:127]
	v_mfma_f32_16x16x32_bf16 v[120:123], v[152:155], v[160:163], v[120:123]
	v_mfma_f32_16x16x32_bf16 v[116:119], v[144:147], v[168:171], v[116:119]
	v_mfma_f32_16x16x32_bf16 v[108:111], v[152:155], v[168:171], v[108:111]
	v_mfma_f32_16x16x32_bf16 v[100:103], v[144:147], v[176:179], v[100:103]
	v_mfma_f32_16x16x32_bf16 v[92:95], v[152:155], v[176:179], v[92:95]
	v_mfma_f32_16x16x32_bf16 v[84:87], v[144:147], v[184:187], v[84:87]
	v_mfma_f32_16x16x32_bf16 v[76:79], v[152:155], v[184:187], v[76:79]
	v_mfma_f32_16x16x32_bf16 v[124:127], v[148:151], v[164:167], v[124:127]
	v_mfma_f32_16x16x32_bf16 v[120:123], v[156:159], v[164:167], v[120:123]
	v_mfma_f32_16x16x32_bf16 v[116:119], v[148:151], v[172:175], v[116:119]
	v_mfma_f32_16x16x32_bf16 v[108:111], v[156:159], v[172:175], v[108:111]
	v_mfma_f32_16x16x32_bf16 v[100:103], v[148:151], v[180:183], v[100:103]
	v_mfma_f32_16x16x32_bf16 v[92:95], v[156:159], v[180:183], v[92:95]
	v_mfma_f32_16x16x32_bf16 v[84:87], v[148:151], v[188:191], v[84:87]
	v_mfma_f32_16x16x32_bf16 v[76:79], v[156:159], v[188:191], v[76:79]
	v_mfma_f32_16x16x32_bf16 v[112:115], v[194:197], v[160:163], v[112:115]
	v_mfma_f32_16x16x32_bf16 v[104:107], v[202:205], v[160:163], v[104:107]
	v_mfma_f32_16x16x32_bf16 v[96:99], v[194:197], v[168:171], v[96:99]
	v_mfma_f32_16x16x32_bf16 v[88:91], v[202:205], v[168:171], v[88:91]
	v_mfma_f32_16x16x32_bf16 v[80:83], v[194:197], v[176:179], v[80:83]
	v_mfma_f32_16x16x32_bf16 v[72:75], v[202:205], v[176:179], v[72:75]
	v_mfma_f32_16x16x32_bf16 v[68:71], v[194:197], v[184:187], v[68:71]
	v_mfma_f32_16x16x32_bf16 v[64:67], v[202:205], v[184:187], v[64:67]
	v_mfma_f32_16x16x32_bf16 v[112:115], v[198:201], v[164:167], v[112:115]
	v_mfma_f32_16x16x32_bf16 v[104:107], v[206:209], v[164:167], v[104:107]
	v_mfma_f32_16x16x32_bf16 v[96:99], v[198:201], v[172:175], v[96:99]
	v_mfma_f32_16x16x32_bf16 v[88:91], v[206:209], v[172:175], v[88:91]
	v_mfma_f32_16x16x32_bf16 v[80:83], v[198:201], v[180:183], v[80:83]
	v_mfma_f32_16x16x32_bf16 v[72:75], v[206:209], v[180:183], v[72:75]
	v_mfma_f32_16x16x32_bf16 v[68:71], v[198:201], v[188:191], v[68:71]
	v_mfma_f32_16x16x32_bf16 v[64:67], v[206:209], v[188:191], v[64:67]
	s_setprio 0
	s_barrier
	ds_read_b128 v[160:163], v142 offset:49152
	ds_read_b128 v[164:167], v142 offset:50176
	ds_read_b128 v[168:171], v142 offset:51200
	ds_read_b128 v[172:175], v142 offset:52224
	ds_read_b128 v[176:179], v142 offset:53248
	ds_read_b128 v[180:183], v142 offset:54272
	ds_read_b128 v[184:187], v142 offset:55296
	ds_read_b128 v[188:191], v142 offset:56320
	s_add_i32 s38, 0, 0x1c000
	s_add_i32 s9, s9, s49
	s_mov_b32 m0, s9
	s_nop 0
	global_load_lds_dwordx4 v192, vcc
	s_add_i32 m0, s9, 0x2000
	s_nop 0
	global_load_lds_dwordx4 v132, vcc
	s_mov_b32 m0, s54
	s_nop 0
	global_load_lds_dwordx4 v128, s[98:99]
	s_mov_b32 m0, s55
	s_nop 0
	global_load_lds_dwordx4 v130, s[98:99]
	s_add_u32 s4, s4, 0x200080
	s_addc_u32 s5, s5, 0
	s_add_i32 s9, s38, s49
	s_mov_b32 m0, s9
	s_nop 0
	global_load_lds_dwordx4 v192, s[4:5]
	s_add_i32 m0, s9, 0x2000
	s_nop 0
	global_load_lds_dwordx4 v132, s[4:5]
	s_waitcnt vmcnt(8)
	s_waitcnt lgkmcnt(0)
	s_barrier
	s_setprio 1
	v_mfma_f32_16x16x32_bf16 v[60:63], v[144:147], v[160:163], v[60:63]
	v_mfma_f32_16x16x32_bf16 v[56:59], v[152:155], v[160:163], v[56:59]
	v_mfma_f32_16x16x32_bf16 v[52:55], v[144:147], v[168:171], v[52:55]
	v_mfma_f32_16x16x32_bf16 v[44:47], v[152:155], v[168:171], v[44:47]
	v_mfma_f32_16x16x32_bf16 v[36:39], v[144:147], v[176:179], v[36:39]
	v_mfma_f32_16x16x32_bf16 v[28:31], v[152:155], v[176:179], v[28:31]
	v_mfma_f32_16x16x32_bf16 v[20:23], v[144:147], v[184:187], v[20:23]
	v_mfma_f32_16x16x32_bf16 v[12:15], v[152:155], v[184:187], v[12:15]
	v_mfma_f32_16x16x32_bf16 v[60:63], v[148:151], v[164:167], v[60:63]
	v_mfma_f32_16x16x32_bf16 v[56:59], v[156:159], v[164:167], v[56:59]
	v_mfma_f32_16x16x32_bf16 v[52:55], v[148:151], v[172:175], v[52:55]
	v_mfma_f32_16x16x32_bf16 v[44:47], v[156:159], v[172:175], v[44:47]
	v_mfma_f32_16x16x32_bf16 v[36:39], v[148:151], v[180:183], v[36:39]
	v_mfma_f32_16x16x32_bf16 v[28:31], v[156:159], v[180:183], v[28:31]
	v_mfma_f32_16x16x32_bf16 v[20:23], v[148:151], v[188:191], v[20:23]
	v_mfma_f32_16x16x32_bf16 v[12:15], v[156:159], v[188:191], v[12:15]
	v_mfma_f32_16x16x32_bf16 v[48:51], v[194:197], v[160:163], v[48:51]
	v_mfma_f32_16x16x32_bf16 v[40:43], v[202:205], v[160:163], v[40:43]
	v_mfma_f32_16x16x32_bf16 v[32:35], v[194:197], v[168:171], v[32:35]
	v_mfma_f32_16x16x32_bf16 v[24:27], v[202:205], v[168:171], v[24:27]
	v_mfma_f32_16x16x32_bf16 v[16:19], v[194:197], v[176:179], v[16:19]
	v_mfma_f32_16x16x32_bf16 v[8:11], v[202:205], v[176:179], v[8:11]
	v_mfma_f32_16x16x32_bf16 v[4:7], v[194:197], v[184:187], v[4:7]
	v_mfma_f32_16x16x32_bf16 v[0:3], v[202:205], v[184:187], v[0:3]
	v_mfma_f32_16x16x32_bf16 v[48:51], v[198:201], v[164:167], v[48:51]
	v_mfma_f32_16x16x32_bf16 v[40:43], v[206:209], v[164:167], v[40:43]
	v_mfma_f32_16x16x32_bf16 v[32:35], v[198:201], v[172:175], v[32:35]
	v_mfma_f32_16x16x32_bf16 v[24:27], v[206:209], v[172:175], v[24:27]
	v_mfma_f32_16x16x32_bf16 v[16:19], v[198:201], v[180:183], v[16:19]
	v_mfma_f32_16x16x32_bf16 v[8:11], v[206:209], v[180:183], v[8:11]
	v_mfma_f32_16x16x32_bf16 v[4:7], v[198:201], v[188:191], v[4:7]
	v_mfma_f32_16x16x32_bf16 v[0:3], v[206:209], v[188:191], v[0:3]
	s_setprio 0
	s_add_u32 s2, s2, 0x100
	s_addc_u32 s3, s3, 0
	s_add_u32 s75, s75, 0x100
	s_addc_u32 s78, s78, 0
	s_cmp_ge_i32 s79, s71
	s_mov_b32 s4, s79
	s_barrier
	s_cbranch_scc0 .LBB0_242
	v_sub_co_u32_e64 v138, s[2:3], s74, 1
	s_nop 0
	v_readfirstlane_b32 s64, v138
	s_lshl_b64 s[4:5], s[64:65], 22
	v_readlane_b32 s38, v252, 9
	v_readlane_b32 s39, v252, 10
	s_add_u32 s4, s38, s4
	s_addc_u32 s5, s39, s5
	s_sub_i32 s9, s69, 32
	s_and_b64 s[2:3], s[2:3], exec
	v_readlane_b32 s38, v252, 7
	s_cselect_b32 s2, s69, s9
	v_readlane_b32 s39, v252, 8
	s_cselect_b32 s5, s39, s5
	s_cselect_b32 s4, s38, s4
	s_ashr_i32 s3, s2, 31
	s_lshl_b64 s[2:3], s[2:3], 20
	s_add_u32 s2, s4, s2
	v_mov_b32 v139, v140
	s_addc_u32 s3, s5, s3
	v_ashrrev_i32_e32 v138, 1, v139
	s_lshl_b32 s4, s66, 8
	v_and_b32_e32 v138, -8, v138
	s_or_b32 s4, s4, s59
	v_add_u32_e32 v138, s4, v138
	v_and_or_b32 v144, v139, 15, s58
	v_ashrrev_i32_e32 v139, 31, v138
	v_ashrrev_i32_e32 v145, 31, v144
	v_lshl_add_u64 v[146:147], v[138:139], 1, s[2:3]
	v_lshlrev_b64 v[138:139], 12, v[144:145]
	v_lshl_add_u64 v[138:139], v[146:147], 0, v[138:139]
	v_cvt_pk_bf16_f32 v124, v124, v125
	v_cvt_pk_bf16_f32 v125, v126, v127
	v_cvt_pk_bf16_f32 v126, v120, v121
	v_cvt_pk_bf16_f32 v127, v122, v123
	global_store_dwordx4 v[138:139], v[124:127], off
	v_cvt_pk_bf16_f32 v112, v112, v113
	v_cvt_pk_bf16_f32 v113, v114, v115
	v_cvt_pk_bf16_f32 v114, v104, v105
	v_or_b32_e32 v104, 16, v144
	v_ashrrev_i32_e32 v105, 31, v104
	v_lshlrev_b64 v[104:105], 12, v[104:105]
	v_cvt_pk_bf16_f32 v115, v106, v107
	global_store_dwordx4 v[138:139], v[112:115], off offset:256
	s_mov_b64 s[2:3], 0x80000
	s_mov_b32 s66, s63
	v_lshl_add_u64 v[112:113], v[146:147], 0, v[104:105]
	v_cvt_pk_bf16_f32 v104, v116, v117
	v_cvt_pk_bf16_f32 v105, v118, v119
	v_cvt_pk_bf16_f32 v106, v108, v109
	v_cvt_pk_bf16_f32 v107, v110, v111
	global_store_dwordx4 v[112:113], v[104:107], off
	v_cvt_pk_bf16_f32 v96, v96, v97
	v_cvt_pk_bf16_f32 v97, v98, v99
	v_cvt_pk_bf16_f32 v98, v88, v89
	v_or_b32_e32 v88, 32, v144
	v_ashrrev_i32_e32 v89, 31, v88
	v_lshlrev_b64 v[88:89], 12, v[88:89]
	v_cvt_pk_bf16_f32 v99, v90, v91
	global_store_dwordx4 v[112:113], v[96:99], off offset:256
	s_mov_b32 s69, s34
	s_mov_b32 s74, s35
	v_lshl_add_u64 v[96:97], v[146:147], 0, v[88:89]
	v_cvt_pk_bf16_f32 v88, v100, v101
	v_cvt_pk_bf16_f32 v89, v102, v103
	v_cvt_pk_bf16_f32 v90, v92, v93
	v_cvt_pk_bf16_f32 v91, v94, v95
	global_store_dwordx4 v[96:97], v[88:91], off
	v_cvt_pk_bf16_f32 v80, v80, v81
	v_cvt_pk_bf16_f32 v81, v82, v83
	v_cvt_pk_bf16_f32 v82, v72, v73
	v_or_b32_e32 v72, 48, v144
	v_ashrrev_i32_e32 v73, 31, v72
	v_lshlrev_b64 v[72:73], 12, v[72:73]
	v_cvt_pk_bf16_f32 v83, v74, v75
	global_store_dwordx4 v[96:97], v[80:83], off offset:256
	s_mov_b32 s71, s67
	s_mov_b64 s[4:5], s[36:37]
	v_lshl_add_u64 v[80:81], v[146:147], 0, v[72:73]
	v_cvt_pk_bf16_f32 v72, v84, v85
	v_cvt_pk_bf16_f32 v73, v86, v87
	v_cvt_pk_bf16_f32 v74, v76, v77
	v_cvt_pk_bf16_f32 v75, v78, v79
	global_store_dwordx4 v[80:81], v[72:75], off
	v_cvt_pk_bf16_f32 v68, v68, v69
	v_cvt_pk_bf16_f32 v69, v70, v71
	v_cvt_pk_bf16_f32 v70, v64, v65
	v_lshl_add_u64 v[64:65], v[138:139], 0, s[2:3]
	s_mov_b32 s2, 0x80000
	v_cvt_pk_bf16_f32 v71, v66, v67
	global_store_dwordx4 v[80:81], v[68:71], off offset:256
	v_cvt_pk_bf16_f32 v60, v60, v61
	v_cvt_pk_bf16_f32 v61, v62, v63
	v_cvt_pk_bf16_f32 v62, v56, v57
	v_add_co_u32_e32 v56, vcc, s2, v138
	v_cvt_pk_bf16_f32 v63, v58, v59
	s_mov_b64 s[2:3], 0x90000
	s_nop 0
	v_addc_co_u32_e32 v57, vcc, 0, v139, vcc
	global_store_dwordx4 v[56:57], v[60:63], off
	v_cvt_pk_bf16_f32 v48, v48, v49
	v_cvt_pk_bf16_f32 v49, v50, v51
	v_cvt_pk_bf16_f32 v50, v40, v41
	v_cvt_pk_bf16_f32 v51, v42, v43
	global_store_dwordx4 v[64:65], v[48:51], off offset:256
	v_cvt_pk_bf16_f32 v40, v52, v53
	v_cvt_pk_bf16_f32 v41, v54, v55
	v_cvt_pk_bf16_f32 v42, v44, v45
	v_cvt_pk_bf16_f32 v43, v46, v47
	s_mov_b64 s[78:79], 0x2000
	s_nop 0
	v_lshl_add_u64 v[48:49], v[138:139], 0, s[2:3]
	s_mov_b32 s2, 0x90000
	v_add_co_u32_e32 v44, vcc, s2, v138
	s_mov_b64 s[2:3], 0xa0000
	s_nop 0
	v_addc_co_u32_e32 v45, vcc, 0, v139, vcc
	global_store_dwordx4 v[44:45], v[40:43], off
	v_cvt_pk_bf16_f32 v32, v32, v33
	v_cvt_pk_bf16_f32 v33, v34, v35
	v_cvt_pk_bf16_f32 v34, v24, v25
	v_cvt_pk_bf16_f32 v35, v26, v27
	global_store_dwordx4 v[48:49], v[32:35], off offset:256
	v_cvt_pk_bf16_f32 v24, v36, v37
	v_cvt_pk_bf16_f32 v25, v38, v39
	v_cvt_pk_bf16_f32 v26, v28, v29
	v_cvt_pk_bf16_f32 v27, v30, v31
	s_nop 1
	v_lshl_add_u64 v[32:33], v[138:139], 0, s[2:3]
	s_mov_b32 s2, 0xa0000
	v_add_co_u32_e32 v28, vcc, s2, v138
	s_mov_b64 s[2:3], 0xb0000
	s_nop 0
	v_addc_co_u32_e32 v29, vcc, 0, v139, vcc
	global_store_dwordx4 v[28:29], v[24:27], off
	v_cvt_pk_bf16_f32 v16, v16, v17
	v_cvt_pk_bf16_f32 v17, v18, v19
	v_cvt_pk_bf16_f32 v18, v8, v9
	v_cvt_pk_bf16_f32 v19, v10, v11
	global_store_dwordx4 v[32:33], v[16:19], off offset:256
	v_cvt_pk_bf16_f32 v8, v20, v21
	v_cvt_pk_bf16_f32 v9, v22, v23
	v_cvt_pk_bf16_f32 v10, v12, v13
	v_cvt_pk_bf16_f32 v11, v14, v15
	s_nop 1
	v_lshl_add_u64 v[16:17], v[138:139], 0, s[2:3]
	s_mov_b32 s2, 0xb0000
	v_add_co_u32_e32 v12, vcc, s2, v138
	s_mov_b64 s[2:3], s[28:29]
	s_nop 0
	v_addc_co_u32_e32 v13, vcc, 0, v139, vcc
	s_and_b64 vcc, exec, s[14:15]
	global_store_dwordx4 v[12:13], v[8:11], off
	v_cvt_pk_bf16_f32 v4, v4, v5
	v_cvt_pk_bf16_f32 v5, v6, v7
	v_cvt_pk_bf16_f32 v6, v0, v1
	v_cvt_pk_bf16_f32 v7, v2, v3
	global_store_dwordx4 v[16:17], v[4:7], off offset:256
	s_cbranch_vccz .LBB0_232
	s_waitcnt vmcnt(0)
	s_cmpk_gt_u32 s40, 0xff
	s_cbranch_scc1 .LBB0_246
	s_barrier

.LBB0_256:
	v_add_u32_e32 v138, 0x10000, v141
	ds_read_b128 v[144:147], v138
	ds_read_b128 v[148:151], v138 offset:1024
	ds_read_b128 v[152:155], v138 offset:2048
	ds_read_b128 v[156:159], v138 offset:3072
	ds_read_b128 v[160:163], v142
	ds_read_b128 v[164:167], v142 offset:1024
	ds_read_b128 v[168:171], v142 offset:2048
	ds_read_b128 v[172:175], v142 offset:3072
	ds_read_b128 v[176:179], v142 offset:4096
	ds_read_b128 v[180:183], v142 offset:5120
	ds_read_b128 v[184:187], v142 offset:6144
	ds_read_b128 v[188:191], v142 offset:7168
	v_add_u32_e32 v138, 0x14000, v141
	ds_read_b128 v[194:197], v138
	ds_read_b128 v[198:201], v138 offset:1024
	ds_read_b128 v[202:205], v138 offset:2048
	ds_read_b128 v[206:209], v138 offset:3072
	s_add_u32 s4, s2, 0xfff80080
	s_addc_u32 s5, s3, -1
	s_add_i32 s9, 0, 0x10000
	s_cmp_eq_u32 s69, 28
	s_cselect_b32 s49, s35, s5
	s_cselect_b32 s48, s34, s4
	s_cselect_b32 s5, s37, s29
	s_cselect_b32 s4, s36, s15
	s_add_i32 m0, s39, 0xc000
	s_nop 0
	global_load_lds_dwordx4 v134, s[2:3]
	s_add_i32 m0, s39, 0xe000
	s_nop 0
	global_load_lds_dwordx4 v136, s[2:3]
	s_waitcnt vmcnt(8)
	s_waitcnt lgkmcnt(0)
	s_barrier
	s_setprio 1
	v_mfma_f32_16x16x32_bf16 v[124:127], v[144:147], v[160:163], v[124:127]
	v_mfma_f32_16x16x32_bf16 v[120:123], v[152:155], v[160:163], v[120:123]
	v_mfma_f32_16x16x32_bf16 v[108:111], v[144:147], v[168:171], v[108:111]
	v_mfma_f32_16x16x32_bf16 v[104:107], v[152:155], v[168:171], v[104:107]
	v_mfma_f32_16x16x32_bf16 v[92:95], v[144:147], v[176:179], v[92:95]
	v_mfma_f32_16x16x32_bf16 v[88:91], v[152:155], v[176:179], v[88:91]
	v_mfma_f32_16x16x32_bf16 v[76:79], v[144:147], v[184:187], v[76:79]
	v_mfma_f32_16x16x32_bf16 v[72:75], v[152:155], v[184:187], v[72:75]
	v_mfma_f32_16x16x32_bf16 v[124:127], v[148:151], v[164:167], v[124:127]
	v_mfma_f32_16x16x32_bf16 v[120:123], v[156:159], v[164:167], v[120:123]
	v_mfma_f32_16x16x32_bf16 v[108:111], v[148:151], v[172:175], v[108:111]
	v_mfma_f32_16x16x32_bf16 v[104:107], v[156:159], v[172:175], v[104:107]
	v_mfma_f32_16x16x32_bf16 v[92:95], v[148:151], v[180:183], v[92:95]
	v_mfma_f32_16x16x32_bf16 v[88:91], v[156:159], v[180:183], v[88:91]
	v_mfma_f32_16x16x32_bf16 v[76:79], v[148:151], v[188:191], v[76:79]
	v_mfma_f32_16x16x32_bf16 v[72:75], v[156:159], v[188:191], v[72:75]
	v_mfma_f32_16x16x32_bf16 v[116:119], v[194:197], v[160:163], v[116:119]
	v_mfma_f32_16x16x32_bf16 v[112:115], v[202:205], v[160:163], v[112:115]
	v_mfma_f32_16x16x32_bf16 v[100:103], v[194:197], v[168:171], v[100:103]
	v_mfma_f32_16x16x32_bf16 v[96:99], v[202:205], v[168:171], v[96:99]
	v_mfma_f32_16x16x32_bf16 v[84:87], v[194:197], v[176:179], v[84:87]
	v_mfma_f32_16x16x32_bf16 v[80:83], v[202:205], v[176:179], v[80:83]
	v_mfma_f32_16x16x32_bf16 v[68:71], v[194:197], v[184:187], v[68:71]
	v_mfma_f32_16x16x32_bf16 v[64:67], v[202:205], v[184:187], v[64:67]
	v_mfma_f32_16x16x32_bf16 v[116:119], v[198:201], v[164:167], v[116:119]
	v_mfma_f32_16x16x32_bf16 v[112:115], v[206:209], v[164:167], v[112:115]
	v_mfma_f32_16x16x32_bf16 v[100:103], v[198:201], v[172:175], v[100:103]
	v_mfma_f32_16x16x32_bf16 v[96:99], v[206:209], v[172:175], v[96:99]
	v_mfma_f32_16x16x32_bf16 v[84:87], v[198:201], v[180:183], v[84:87]
	v_mfma_f32_16x16x32_bf16 v[80:83], v[206:209], v[180:183], v[80:83]
	v_mfma_f32_16x16x32_bf16 v[68:71], v[198:201], v[188:191], v[68:71]
	v_mfma_f32_16x16x32_bf16 v[64:67], v[206:209], v[188:191], v[64:67]
	s_setprio 0
	s_barrier
	ds_read_b128 v[160:163], v142 offset:16384
	ds_read_b128 v[164:167], v142 offset:17408
	ds_read_b128 v[168:171], v142 offset:18432
	ds_read_b128 v[172:175], v142 offset:19456
	ds_read_b128 v[176:179], v142 offset:20480
	ds_read_b128 v[180:183], v142 offset:21504
	ds_read_b128 v[184:187], v142 offset:22528
	ds_read_b128 v[188:191], v142 offset:23552
	s_add_i32 s71, 0, 0x14000
	s_add_i32 s9, s9, s50
	s_add_u32 vcc_lo, s4, 0x80
	s_addc_u32 vcc_hi, s5, 0
	s_mov_b32 m0, s9
	s_nop 0
	global_load_lds_dwordx4 v192, s[4:5]
	s_add_i32 m0, s9, 0x2000
	s_nop 0
	global_load_lds_dwordx4 v128, s[4:5]
	s_mov_b32 m0, s39
	s_add_u32 s98, s48, 0x80
	s_addc_u32 s99, s49, 0
	global_load_lds_dwordx4 v132, s[48:49]
	s_mov_b32 m0, s54
	s_nop 0
	global_load_lds_dwordx4 v130, s[48:49]
	s_add_u32 s46, s4, 0x80000
	s_addc_u32 s47, s5, 0
	s_add_i32 s9, s71, s50
	s_mov_b32 m0, s9
	s_nop 0
	global_load_lds_dwordx4 v192, s[46:47]
	s_add_i32 m0, s9, 0x2000
	s_nop 0
	global_load_lds_dwordx4 v128, s[46:47]
	s_waitcnt vmcnt(8)
	s_waitcnt lgkmcnt(0)
	s_barrier
	s_setprio 1
	v_mfma_f32_16x16x32_bf16 v[60:63], v[144:147], v[160:163], v[60:63]
	v_mfma_f32_16x16x32_bf16 v[56:59], v[152:155], v[160:163], v[56:59]
	v_mfma_f32_16x16x32_bf16 v[44:47], v[144:147], v[168:171], v[44:47]
	v_mfma_f32_16x16x32_bf16 v[40:43], v[152:155], v[168:171], v[40:43]
	v_mfma_f32_16x16x32_bf16 v[28:31], v[144:147], v[176:179], v[28:31]
	v_mfma_f32_16x16x32_bf16 v[24:27], v[152:155], v[176:179], v[24:27]
	v_mfma_f32_16x16x32_bf16 v[12:15], v[144:147], v[184:187], v[12:15]
	v_mfma_f32_16x16x32_bf16 v[8:11], v[152:155], v[184:187], v[8:11]
	v_mfma_f32_16x16x32_bf16 v[60:63], v[148:151], v[164:167], v[60:63]
	v_mfma_f32_16x16x32_bf16 v[56:59], v[156:159], v[164:167], v[56:59]
	v_mfma_f32_16x16x32_bf16 v[44:47], v[148:151], v[172:175], v[44:47]
	v_mfma_f32_16x16x32_bf16 v[40:43], v[156:159], v[172:175], v[40:43]
	v_mfma_f32_16x16x32_bf16 v[28:31], v[148:151], v[180:183], v[28:31]
	v_mfma_f32_16x16x32_bf16 v[24:27], v[156:159], v[180:183], v[24:27]
	v_mfma_f32_16x16x32_bf16 v[12:15], v[148:151], v[188:191], v[12:15]
	v_mfma_f32_16x16x32_bf16 v[8:11], v[156:159], v[188:191], v[8:11]
	v_mfma_f32_16x16x32_bf16 v[52:55], v[194:197], v[160:163], v[52:55]
	v_mfma_f32_16x16x32_bf16 v[48:51], v[202:205], v[160:163], v[48:51]
	v_mfma_f32_16x16x32_bf16 v[36:39], v[194:197], v[168:171], v[36:39]
	v_mfma_f32_16x16x32_bf16 v[32:35], v[202:205], v[168:171], v[32:35]
	v_mfma_f32_16x16x32_bf16 v[20:23], v[194:197], v[176:179], v[20:23]
	v_mfma_f32_16x16x32_bf16 v[16:19], v[202:205], v[176:179], v[16:19]
	v_mfma_f32_16x16x32_bf16 v[4:7], v[194:197], v[184:187], v[4:7]
	v_mfma_f32_16x16x32_bf16 v[0:3], v[202:205], v[184:187], v[0:3]
	v_mfma_f32_16x16x32_bf16 v[52:55], v[198:201], v[164:167], v[52:55]
	v_mfma_f32_16x16x32_bf16 v[48:51], v[206:209], v[164:167], v[48:51]
	v_mfma_f32_16x16x32_bf16 v[36:39], v[198:201], v[172:175], v[36:39]
	v_mfma_f32_16x16x32_bf16 v[32:35], v[206:209], v[172:175], v[32:35]
	v_mfma_f32_16x16x32_bf16 v[20:23], v[198:201], v[180:183], v[20:23]
	v_mfma_f32_16x16x32_bf16 v[16:19], v[206:209], v[180:183], v[16:19]
	v_mfma_f32_16x16x32_bf16 v[4:7], v[198:201], v[188:191], v[4:7]
	v_mfma_f32_16x16x32_bf16 v[0:3], v[206:209], v[188:191], v[0:3]
	s_setprio 0
	s_barrier
	v_add_u32_e32 v143, 0x18000, v141
	ds_read_b128 v[144:147], v143
	ds_read_b128 v[148:151], v143 offset:1024
	ds_read_b128 v[152:155], v143 offset:2048
	ds_read_b128 v[156:159], v143 offset:3072
	ds_read_b128 v[160:163], v142 offset:32768
	ds_read_b128 v[164:167], v142 offset:33792
	ds_read_b128 v[168:171], v142 offset:34816
	ds_read_b128 v[172:175], v142 offset:35840
	ds_read_b128 v[176:179], v142 offset:36864
	ds_read_b128 v[180:183], v142 offset:37888
	ds_read_b128 v[184:187], v142 offset:38912
	ds_read_b128 v[188:191], v142 offset:39936
	v_add_u32_e32 v143, 0x1c000, v141
	ds_read_b128 v[194:197], v143
	ds_read_b128 v[198:201], v143 offset:1024
	ds_read_b128 v[202:205], v143 offset:2048
	ds_read_b128 v[206:209], v143 offset:3072
	s_add_i32 s9, 0, 0x18000
	s_add_u32 s46, s48, 0x80000
	s_addc_u32 s47, s49, 0
	s_mov_b32 m0, s55
	s_nop 0
	global_load_lds_dwordx4 v132, s[46:47]
	s_mov_b32 m0, s58
	s_nop 0
	global_load_lds_dwordx4 v130, s[46:47]
	s_waitcnt vmcnt(8)
	s_waitcnt lgkmcnt(0)
	s_barrier
	s_setprio 1
	v_mfma_f32_16x16x32_bf16 v[124:127], v[144:147], v[160:163], v[124:127]
	v_mfma_f32_16x16x32_bf16 v[120:123], v[152:155], v[160:163], v[120:123]
	v_mfma_f32_16x16x32_bf16 v[108:111], v[144:147], v[168:171], v[108:111]
	v_mfma_f32_16x16x32_bf16 v[104:107], v[152:155], v[168:171], v[104:107]
	v_mfma_f32_16x16x32_bf16 v[92:95], v[144:147], v[176:179], v[92:95]
	v_mfma_f32_16x16x32_bf16 v[88:91], v[152:155], v[176:179], v[88:91]
	v_mfma_f32_16x16x32_bf16 v[76:79], v[144:147], v[184:187], v[76:79]
	v_mfma_f32_16x16x32_bf16 v[72:75], v[152:155], v[184:187], v[72:75]
	v_mfma_f32_16x16x32_bf16 v[124:127], v[148:151], v[164:167], v[124:127]
	v_mfma_f32_16x16x32_bf16 v[120:123], v[156:159], v[164:167], v[120:123]
	v_mfma_f32_16x16x32_bf16 v[108:111], v[148:151], v[172:175], v[108:111]
	v_mfma_f32_16x16x32_bf16 v[104:107], v[156:159], v[172:175], v[104:107]
	v_mfma_f32_16x16x32_bf16 v[92:95], v[148:151], v[180:183], v[92:95]
	v_mfma_f32_16x16x32_bf16 v[88:91], v[156:159], v[180:183], v[88:91]
	v_mfma_f32_16x16x32_bf16 v[76:79], v[148:151], v[188:191], v[76:79]
	v_mfma_f32_16x16x32_bf16 v[72:75], v[156:159], v[188:191], v[72:75]
	v_mfma_f32_16x16x32_bf16 v[116:119], v[194:197], v[160:163], v[116:119]
	v_mfma_f32_16x16x32_bf16 v[112:115], v[202:205], v[160:163], v[112:115]
	v_mfma_f32_16x16x32_bf16 v[100:103], v[194:197], v[168:171], v[100:103]
	v_mfma_f32_16x16x32_bf16 v[96:99], v[202:205], v[168:171], v[96:99]
	v_mfma_f32_16x16x32_bf16 v[84:87], v[194:197], v[176:179], v[84:87]
	v_mfma_f32_16x16x32_bf16 v[80:83], v[202:205], v[176:179], v[80:83]
	v_mfma_f32_16x16x32_bf16 v[68:71], v[194:197], v[184:187], v[68:71]
	v_mfma_f32_16x16x32_bf16 v[64:67], v[202:205], v[184:187], v[64:67]
	v_mfma_f32_16x16x32_bf16 v[116:119], v[198:201], v[164:167], v[116:119]
	v_mfma_f32_16x16x32_bf16 v[112:115], v[206:209], v[164:167], v[112:115]
	v_mfma_f32_16x16x32_bf16 v[100:103], v[198:201], v[172:175], v[100:103]
	v_mfma_f32_16x16x32_bf16 v[96:99], v[206:209], v[172:175], v[96:99]
	v_mfma_f32_16x16x32_bf16 v[84:87], v[198:201], v[180:183], v[84:87]
	v_mfma_f32_16x16x32_bf16 v[80:83], v[206:209], v[180:183], v[80:83]
	v_mfma_f32_16x16x32_bf16 v[68:71], v[198:201], v[188:191], v[68:71]
	v_mfma_f32_16x16x32_bf16 v[64:67], v[206:209], v[188:191], v[64:67]
	s_setprio 0
	s_barrier
	ds_read_b128 v[160:163], v142 offset:49152
	ds_read_b128 v[164:167], v142 offset:50176
	ds_read_b128 v[168:171], v142 offset:51200
	ds_read_b128 v[172:175], v142 offset:52224
	ds_read_b128 v[176:179], v142 offset:53248
	ds_read_b128 v[180:183], v142 offset:54272
	ds_read_b128 v[184:187], v142 offset:55296
	ds_read_b128 v[188:191], v142 offset:56320
	s_add_i32 s46, 0, 0x1c000
	s_add_i32 s9, s9, s50
	s_mov_b32 m0, s9
	s_nop 0
	global_load_lds_dwordx4 v192, vcc
	s_add_i32 m0, s9, 0x2000
	s_nop 0
	global_load_lds_dwordx4 v128, vcc
	s_mov_b32 m0, s59
	s_nop 0
	global_load_lds_dwordx4 v132, s[98:99]
	s_mov_b32 m0, s62
	s_nop 0
	global_load_lds_dwordx4 v130, s[98:99]
	s_add_u32 s4, s4, 0x80080
	s_addc_u32 s5, s5, 0
	s_add_i32 s9, s46, s50
	s_mov_b32 m0, s9
	s_nop 0
	global_load_lds_dwordx4 v192, s[4:5]
	s_add_i32 m0, s9, 0x2000
	s_nop 0
	global_load_lds_dwordx4 v128, s[4:5]
	s_waitcnt vmcnt(8)
	s_waitcnt lgkmcnt(0)
	s_barrier
	s_setprio 1
	v_mfma_f32_16x16x32_bf16 v[60:63], v[144:147], v[160:163], v[60:63]
	v_mfma_f32_16x16x32_bf16 v[56:59], v[152:155], v[160:163], v[56:59]
	v_mfma_f32_16x16x32_bf16 v[44:47], v[144:147], v[168:171], v[44:47]
	v_mfma_f32_16x16x32_bf16 v[40:43], v[152:155], v[168:171], v[40:43]
	v_mfma_f32_16x16x32_bf16 v[28:31], v[144:147], v[176:179], v[28:31]
	v_mfma_f32_16x16x32_bf16 v[24:27], v[152:155], v[176:179], v[24:27]
	v_mfma_f32_16x16x32_bf16 v[12:15], v[144:147], v[184:187], v[12:15]
	v_mfma_f32_16x16x32_bf16 v[8:11], v[152:155], v[184:187], v[8:11]
	v_mfma_f32_16x16x32_bf16 v[60:63], v[148:151], v[164:167], v[60:63]
	v_mfma_f32_16x16x32_bf16 v[56:59], v[156:159], v[164:167], v[56:59]
	v_mfma_f32_16x16x32_bf16 v[44:47], v[148:151], v[172:175], v[44:47]
	v_mfma_f32_16x16x32_bf16 v[40:43], v[156:159], v[172:175], v[40:43]
	v_mfma_f32_16x16x32_bf16 v[28:31], v[148:151], v[180:183], v[28:31]
	v_mfma_f32_16x16x32_bf16 v[24:27], v[156:159], v[180:183], v[24:27]
	v_mfma_f32_16x16x32_bf16 v[12:15], v[148:151], v[188:191], v[12:15]
	v_mfma_f32_16x16x32_bf16 v[8:11], v[156:159], v[188:191], v[8:11]
	v_mfma_f32_16x16x32_bf16 v[52:55], v[194:197], v[160:163], v[52:55]
	v_mfma_f32_16x16x32_bf16 v[48:51], v[202:205], v[160:163], v[48:51]
	v_mfma_f32_16x16x32_bf16 v[36:39], v[194:197], v[168:171], v[36:39]
	v_mfma_f32_16x16x32_bf16 v[32:35], v[202:205], v[168:171], v[32:35]
	v_mfma_f32_16x16x32_bf16 v[20:23], v[194:197], v[176:179], v[20:23]
	v_mfma_f32_16x16x32_bf16 v[16:19], v[202:205], v[176:179], v[16:19]
	v_mfma_f32_16x16x32_bf16 v[4:7], v[194:197], v[184:187], v[4:7]
	v_mfma_f32_16x16x32_bf16 v[0:3], v[202:205], v[184:187], v[0:3]
	v_mfma_f32_16x16x32_bf16 v[52:55], v[198:201], v[164:167], v[52:55]
	v_mfma_f32_16x16x32_bf16 v[48:51], v[206:209], v[164:167], v[48:51]
	v_mfma_f32_16x16x32_bf16 v[36:39], v[198:201], v[172:175], v[36:39]
	v_mfma_f32_16x16x32_bf16 v[32:35], v[206:209], v[172:175], v[32:35]
	v_mfma_f32_16x16x32_bf16 v[20:23], v[198:201], v[180:183], v[20:23]
	v_mfma_f32_16x16x32_bf16 v[16:19], v[206:209], v[180:183], v[16:19]
	v_mfma_f32_16x16x32_bf16 v[4:7], v[198:201], v[188:191], v[4:7]
	v_mfma_f32_16x16x32_bf16 v[0:3], v[206:209], v[188:191], v[0:3]
	s_setprio 0
	s_add_i32 s69, s69, 2
	s_add_u32 s2, s2, 0x100
	s_addc_u32 s3, s3, 0
	s_add_u32 s15, s15, 0x100
	s_addc_u32 s29, s29, 0
	s_cmp_gt_u32 s69, 29
	s_barrier
	s_cbranch_scc0 .LBB0_256
	s_lshl_b32 s2, s38, 8
	v_mov_b32 v138, v140
	s_add_i32 s2, s2, s63
	v_and_or_b32 v144, v138, 15, s2
	s_lshl_b32 s2, s67, 8
	v_ashrrev_i32_e32 v138, 1, v138
	v_max_f32_e32 v120, v120, v120
	s_or_b32 s2, s2, s64
	v_and_b32_e32 v138, -8, v138
	v_max_f32_e32 v120, 0, v120
	v_max_f32_e32 v121, v121, v121
	v_max_f32_e32 v122, v122, v122
	v_add_u32_e32 v138, s2, v138
	v_ashrrev_i32_e32 v145, 31, v144
	v_readlane_b32 s2, v252, 63
	v_mul_f32_e32 v143, v120, v120
	v_max_f32_e32 v120, v125, v125
	v_max_f32_e32 v121, 0, v121
	v_max_f32_e32 v122, 0, v122
	v_ashrrev_i32_e32 v139, 31, v138
	v_lshlrev_b64 v[146:147], 14, v[144:145]
	v_readlane_b32 s3, v253, 0
	v_max_f32_e32 v124, v124, v124
	v_max_f32_e32 v120, 0, v120
	v_mul_f32_e32 v125, v121, v121
	v_max_f32_e32 v121, v126, v126
	v_mul_f32_e32 v126, v122, v122
	v_max_f32_e32 v122, v127, v127
	v_max_f32_e32 v123, v123, v123
	v_lshl_add_u64 v[146:147], s[2:3], 0, v[146:147]
	v_lshlrev_b64 v[148:149], 1, v[138:139]
	v_max_f32_e32 v124, 0, v124
	v_mul_f32_e32 v120, v120, v120
	v_max_f32_e32 v121, 0, v121
	v_max_f32_e32 v122, 0, v122
	v_max_f32_e32 v123, 0, v123
	v_max_f32_e32 v112, v112, v112
	v_lshl_add_u64 v[138:139], v[146:147], 0, v[148:149]
	v_mul_f32_e32 v124, v124, v124
	v_mul_f32_e32 v121, v121, v121
	v_mul_f32_e32 v122, v122, v122
	v_mul_f32_e32 v123, v123, v123
	v_cvt_pk_bf16_f32 v120, v124, v120
	v_max_f32_e32 v112, 0, v112
	v_max_f32_e32 v113, v113, v113
	v_max_f32_e32 v114, v114, v114
	v_cvt_pk_bf16_f32 v121, v121, v122
	v_cvt_pk_bf16_f32 v122, v143, v125
	v_cvt_pk_bf16_f32 v123, v126, v123
	global_store_dwordx4 v[138:139], v[120:123], off
	v_max_f32_e32 v113, 0, v113
	v_max_f32_e32 v114, 0, v114
	v_mul_f32_e32 v120, v112, v112
	v_max_f32_e32 v112, v117, v117
	v_max_f32_e32 v116, v116, v116
	v_max_f32_e32 v112, 0, v112
	v_mul_f32_e32 v117, v113, v113
	v_max_f32_e32 v113, v118, v118
	v_mul_f32_e32 v118, v114, v114
	v_max_f32_e32 v114, v119, v119
	v_max_f32_e32 v115, v115, v115
	v_max_f32_e32 v116, 0, v116
	v_mul_f32_e32 v112, v112, v112
	v_max_f32_e32 v113, 0, v113
	v_max_f32_e32 v114, 0, v114
	v_max_f32_e32 v115, 0, v115
	v_mul_f32_e32 v116, v116, v116
	v_mul_f32_e32 v113, v113, v113
	v_mul_f32_e32 v114, v114, v114
	v_mul_f32_e32 v115, v115, v115
	v_cvt_pk_bf16_f32 v112, v116, v112
	v_max_f32_e32 v104, v104, v104
	v_cvt_pk_bf16_f32 v113, v113, v114
	v_cvt_pk_bf16_f32 v114, v120, v117
	v_cvt_pk_bf16_f32 v115, v118, v115
	global_store_dwordx4 v[138:139], v[112:115], off offset:256
	v_max_f32_e32 v104, 0, v104
	v_max_f32_e32 v105, v105, v105
	v_or_b32_e32 v112, 16, v144
	v_max_f32_e32 v106, v106, v106
	v_ashrrev_i32_e32 v113, 31, v112
	v_mul_f32_e32 v114, v104, v104
	v_max_f32_e32 v104, v109, v109
	v_max_f32_e32 v105, 0, v105
	v_max_f32_e32 v106, 0, v106
	v_lshlrev_b64 v[112:113], 14, v[112:113]
	v_max_f32_e32 v108, v108, v108
	v_max_f32_e32 v104, 0, v104
	v_mul_f32_e32 v109, v105, v105
	v_max_f32_e32 v105, v110, v110
	v_mul_f32_e32 v110, v106, v106
	v_max_f32_e32 v106, v111, v111
	v_max_f32_e32 v107, v107, v107
	v_lshl_add_u64 v[112:113], s[2:3], 0, v[112:113]
	v_max_f32_e32 v108, 0, v108
	v_mul_f32_e32 v104, v104, v104
	v_max_f32_e32 v105, 0, v105
	v_max_f32_e32 v106, 0, v106
	v_max_f32_e32 v107, 0, v107
	v_max_f32_e32 v96, v96, v96
	v_lshl_add_u64 v[112:113], v[112:113], 0, v[148:149]
	v_mul_f32_e32 v108, v108, v108
	v_mul_f32_e32 v105, v105, v105
	v_mul_f32_e32 v106, v106, v106
	v_mul_f32_e32 v107, v107, v107
	v_cvt_pk_bf16_f32 v104, v108, v104
	v_max_f32_e32 v96, 0, v96
	v_max_f32_e32 v97, v97, v97
	v_max_f32_e32 v98, v98, v98
	v_cvt_pk_bf16_f32 v105, v105, v106
	v_cvt_pk_bf16_f32 v106, v114, v109
	v_cvt_pk_bf16_f32 v107, v110, v107
	global_store_dwordx4 v[112:113], v[104:107], off
	v_max_f32_e32 v97, 0, v97
	v_max_f32_e32 v98, 0, v98
	v_mul_f32_e32 v104, v96, v96
	v_max_f32_e32 v96, v101, v101
	v_max_f32_e32 v100, v100, v100
	v_max_f32_e32 v96, 0, v96
	v_mul_f32_e32 v101, v97, v97
	v_max_f32_e32 v97, v102, v102
	v_mul_f32_e32 v102, v98, v98
	v_max_f32_e32 v98, v103, v103
	v_max_f32_e32 v99, v99, v99
	v_max_f32_e32 v100, 0, v100
	v_mul_f32_e32 v96, v96, v96
	v_max_f32_e32 v97, 0, v97
	v_max_f32_e32 v98, 0, v98
	v_max_f32_e32 v99, 0, v99
	v_mul_f32_e32 v100, v100, v100
	v_mul_f32_e32 v97, v97, v97
	v_mul_f32_e32 v98, v98, v98
	v_mul_f32_e32 v99, v99, v99
	v_cvt_pk_bf16_f32 v96, v100, v96
	v_max_f32_e32 v88, v88, v88
	v_cvt_pk_bf16_f32 v97, v97, v98
	v_cvt_pk_bf16_f32 v98, v104, v101
	v_cvt_pk_bf16_f32 v99, v102, v99
	global_store_dwordx4 v[112:113], v[96:99], off offset:256
	v_max_f32_e32 v88, 0, v88
	v_max_f32_e32 v89, v89, v89
	v_or_b32_e32 v96, 32, v144
	v_max_f32_e32 v90, v90, v90
	v_ashrrev_i32_e32 v97, 31, v96
	v_mul_f32_e32 v98, v88, v88
	v_max_f32_e32 v88, v93, v93
	v_max_f32_e32 v89, 0, v89
	v_max_f32_e32 v90, 0, v90
	v_lshlrev_b64 v[96:97], 14, v[96:97]
	v_max_f32_e32 v92, v92, v92
	v_max_f32_e32 v88, 0, v88
	v_mul_f32_e32 v93, v89, v89
	v_max_f32_e32 v89, v94, v94
	v_mul_f32_e32 v94, v90, v90
	v_max_f32_e32 v90, v95, v95
	v_max_f32_e32 v91, v91, v91
	v_lshl_add_u64 v[96:97], s[2:3], 0, v[96:97]
	v_max_f32_e32 v92, 0, v92
	v_mul_f32_e32 v88, v88, v88
	v_max_f32_e32 v89, 0, v89
	v_max_f32_e32 v90, 0, v90
	v_max_f32_e32 v91, 0, v91
	v_max_f32_e32 v80, v80, v80
	v_lshl_add_u64 v[96:97], v[96:97], 0, v[148:149]
	v_mul_f32_e32 v92, v92, v92
	v_mul_f32_e32 v89, v89, v89
	v_mul_f32_e32 v90, v90, v90
	v_mul_f32_e32 v91, v91, v91
	v_cvt_pk_bf16_f32 v88, v92, v88
	v_max_f32_e32 v80, 0, v80
	v_max_f32_e32 v81, v81, v81
	v_max_f32_e32 v82, v82, v82
	v_cvt_pk_bf16_f32 v89, v89, v90
	v_cvt_pk_bf16_f32 v90, v98, v93
	v_cvt_pk_bf16_f32 v91, v94, v91
	global_store_dwordx4 v[96:97], v[88:91], off
	v_max_f32_e32 v81, 0, v81
	v_max_f32_e32 v82, 0, v82
	v_mul_f32_e32 v88, v80, v80
	v_max_f32_e32 v80, v85, v85
	v_max_f32_e32 v84, v84, v84
	v_max_f32_e32 v80, 0, v80
	v_mul_f32_e32 v85, v81, v81
	v_max_f32_e32 v81, v86, v86
	v_mul_f32_e32 v86, v82, v82
	v_max_f32_e32 v82, v87, v87
	v_max_f32_e32 v83, v83, v83
	v_max_f32_e32 v84, 0, v84
	v_mul_f32_e32 v80, v80, v80
	v_max_f32_e32 v81, 0, v81
	v_max_f32_e32 v82, 0, v82
	v_max_f32_e32 v83, 0, v83
	v_mul_f32_e32 v84, v84, v84
	v_mul_f32_e32 v81, v81, v81
	v_mul_f32_e32 v82, v82, v82
	v_mul_f32_e32 v83, v83, v83
	v_cvt_pk_bf16_f32 v80, v84, v80
	v_max_f32_e32 v72, v72, v72
	v_cvt_pk_bf16_f32 v81, v81, v82
	v_cvt_pk_bf16_f32 v82, v88, v85
	v_cvt_pk_bf16_f32 v83, v86, v83
	global_store_dwordx4 v[96:97], v[80:83], off offset:256
	v_max_f32_e32 v72, 0, v72
	v_max_f32_e32 v73, v73, v73
	v_or_b32_e32 v80, 48, v144
	v_max_f32_e32 v74, v74, v74
	v_ashrrev_i32_e32 v81, 31, v80
	v_mul_f32_e32 v82, v72, v72
	v_max_f32_e32 v72, v77, v77
	v_max_f32_e32 v73, 0, v73
	v_max_f32_e32 v74, 0, v74
	v_lshlrev_b64 v[80:81], 14, v[80:81]
	v_max_f32_e32 v76, v76, v76
	v_max_f32_e32 v72, 0, v72
	v_mul_f32_e32 v77, v73, v73
	v_max_f32_e32 v73, v78, v78
	v_mul_f32_e32 v78, v74, v74
	v_max_f32_e32 v74, v79, v79
	v_max_f32_e32 v75, v75, v75
	v_lshl_add_u64 v[80:81], s[2:3], 0, v[80:81]
	v_max_f32_e32 v76, 0, v76
	v_mul_f32_e32 v72, v72, v72
	v_max_f32_e32 v73, 0, v73
	v_max_f32_e32 v74, 0, v74
	v_max_f32_e32 v75, 0, v75
	v_max_f32_e32 v64, v64, v64
	v_max_f32_e32 v65, v65, v65
	v_max_f32_e32 v66, v66, v66
	v_lshl_add_u64 v[80:81], v[80:81], 0, v[148:149]
	v_mul_f32_e32 v76, v76, v76
	v_mul_f32_e32 v73, v73, v73
	v_mul_f32_e32 v74, v74, v74
	v_mul_f32_e32 v75, v75, v75
	v_cvt_pk_bf16_f32 v72, v76, v72
	v_max_f32_e32 v64, 0, v64
	v_max_f32_e32 v65, 0, v65
	v_max_f32_e32 v66, 0, v66
	v_cvt_pk_bf16_f32 v73, v73, v74
	v_cvt_pk_bf16_f32 v74, v82, v77
	v_cvt_pk_bf16_f32 v75, v78, v75
	global_store_dwordx4 v[80:81], v[72:75], off
	v_max_f32_e32 v68, v68, v68
	v_max_f32_e32 v67, v67, v67
	v_mul_f32_e32 v72, v64, v64
	v_max_f32_e32 v64, v69, v69
	v_mul_f32_e32 v69, v65, v65
	v_max_f32_e32 v65, v70, v70
	v_mul_f32_e32 v70, v66, v66
	v_max_f32_e32 v66, v71, v71
	v_max_f32_e32 v64, 0, v64
	v_max_f32_e32 v65, 0, v65
	v_max_f32_e32 v66, 0, v66
	v_max_f32_e32 v68, 0, v68
	v_mul_f32_e32 v64, v64, v64
	v_mul_f32_e32 v65, v65, v65
	v_max_f32_e32 v67, 0, v67
	v_mul_f32_e32 v66, v66, v66
	v_max_f32_e32 v56, v56, v56
	v_mul_f32_e32 v68, v68, v68
	v_mul_f32_e32 v67, v67, v67
	v_cvt_pk_bf16_f32 v64, v68, v64
	v_cvt_pk_bf16_f32 v65, v65, v66
	v_cvt_pk_bf16_f32 v66, v72, v69
	v_max_f32_e32 v56, 0, v56
	v_max_f32_e32 v57, v57, v57
	v_max_f32_e32 v58, v58, v58
	v_cvt_pk_bf16_f32 v67, v70, v67
	global_store_dwordx4 v[80:81], v[64:67], off offset:256
	v_max_f32_e32 v60, v60, v60
	v_max_f32_e32 v57, 0, v57
	v_mul_f32_e32 v66, v56, v56
	v_max_f32_e32 v56, v61, v61
	v_max_f32_e32 v58, 0, v58
	s_mov_b64 s[2:3], 0x200000
	v_max_f32_e32 v60, 0, v60
	v_max_f32_e32 v56, 0, v56
	v_mul_f32_e32 v61, v57, v57
	v_max_f32_e32 v57, v62, v62
	v_mul_f32_e32 v62, v58, v58
	v_max_f32_e32 v58, v63, v63
	v_lshl_add_u64 v[64:65], v[138:139], 0, s[2:3]
	v_mul_f32_e32 v60, v60, v60
	v_mul_f32_e32 v56, v56, v56
	v_max_f32_e32 v57, 0, v57
	v_max_f32_e32 v58, 0, v58
	v_max_f32_e32 v59, v59, v59
	s_mov_b32 s2, 0x200000
	v_mul_f32_e32 v57, v57, v57
	v_max_f32_e32 v59, 0, v59
	v_mul_f32_e32 v58, v58, v58
	v_cvt_pk_bf16_f32 v56, v60, v56
	v_add_co_u32_e32 v60, vcc, s2, v138
	v_max_f32_e32 v48, v48, v48
	v_max_f32_e32 v49, v49, v49
	v_max_f32_e32 v50, v50, v50
	v_mul_f32_e32 v59, v59, v59
	v_cvt_pk_bf16_f32 v57, v57, v58
	v_cvt_pk_bf16_f32 v58, v66, v61
	v_addc_co_u32_e32 v61, vcc, 0, v139, vcc
	v_max_f32_e32 v48, 0, v48
	v_max_f32_e32 v49, 0, v49
	v_max_f32_e32 v50, 0, v50
	v_cvt_pk_bf16_f32 v59, v62, v59
	global_store_dwordx4 v[60:61], v[56:59], off
	v_max_f32_e32 v52, v52, v52
	v_max_f32_e32 v51, v51, v51
	v_mul_f32_e32 v56, v48, v48
	v_max_f32_e32 v48, v53, v53
	v_mul_f32_e32 v53, v49, v49
	v_max_f32_e32 v49, v54, v54
	v_mul_f32_e32 v54, v50, v50
	v_max_f32_e32 v50, v55, v55
	v_max_f32_e32 v48, 0, v48
	v_max_f32_e32 v49, 0, v49
	v_max_f32_e32 v50, 0, v50
	v_max_f32_e32 v52, 0, v52
	v_mul_f32_e32 v48, v48, v48
	v_mul_f32_e32 v49, v49, v49
	v_max_f32_e32 v51, 0, v51
	v_mul_f32_e32 v50, v50, v50
	v_max_f32_e32 v40, v40, v40
	v_mul_f32_e32 v52, v52, v52
	v_mul_f32_e32 v51, v51, v51
	v_cvt_pk_bf16_f32 v48, v52, v48
	v_cvt_pk_bf16_f32 v49, v49, v50
	v_cvt_pk_bf16_f32 v50, v56, v53
	v_max_f32_e32 v40, 0, v40
	v_max_f32_e32 v41, v41, v41
	v_max_f32_e32 v42, v42, v42
	v_cvt_pk_bf16_f32 v51, v54, v51
	global_store_dwordx4 v[64:65], v[48:51], off offset:256
	v_max_f32_e32 v44, v44, v44
	v_max_f32_e32 v41, 0, v41
	v_mul_f32_e32 v50, v40, v40
	v_max_f32_e32 v40, v45, v45
	v_max_f32_e32 v42, 0, v42
	s_mov_b64 s[2:3], 0x240000
	v_max_f32_e32 v44, 0, v44
	v_max_f32_e32 v40, 0, v40
	v_mul_f32_e32 v45, v41, v41
	v_max_f32_e32 v41, v46, v46
	v_mul_f32_e32 v46, v42, v42
	v_max_f32_e32 v42, v47, v47
	v_lshl_add_u64 v[48:49], v[138:139], 0, s[2:3]
	v_mul_f32_e32 v44, v44, v44
	v_mul_f32_e32 v40, v40, v40
	v_max_f32_e32 v41, 0, v41
	v_max_f32_e32 v42, 0, v42
	v_max_f32_e32 v43, v43, v43
	s_mov_b32 s2, 0x240000
	v_mul_f32_e32 v41, v41, v41
	v_max_f32_e32 v43, 0, v43
	v_mul_f32_e32 v42, v42, v42
	v_cvt_pk_bf16_f32 v40, v44, v40
	v_add_co_u32_e32 v44, vcc, s2, v138
	v_max_f32_e32 v32, v32, v32
	v_max_f32_e32 v33, v33, v33
	v_max_f32_e32 v34, v34, v34
	v_mul_f32_e32 v43, v43, v43
	v_cvt_pk_bf16_f32 v41, v41, v42
	v_cvt_pk_bf16_f32 v42, v50, v45
	v_addc_co_u32_e32 v45, vcc, 0, v139, vcc
	v_max_f32_e32 v32, 0, v32
	v_max_f32_e32 v33, 0, v33
	v_max_f32_e32 v34, 0, v34
	v_cvt_pk_bf16_f32 v43, v46, v43
	global_store_dwordx4 v[44:45], v[40:43], off
	v_max_f32_e32 v36, v36, v36
	v_max_f32_e32 v35, v35, v35
	v_mul_f32_e32 v40, v32, v32
	v_max_f32_e32 v32, v37, v37
	v_mul_f32_e32 v37, v33, v33
	v_max_f32_e32 v33, v38, v38
	v_mul_f32_e32 v38, v34, v34
	v_max_f32_e32 v34, v39, v39
	v_max_f32_e32 v32, 0, v32
	v_max_f32_e32 v33, 0, v33
	v_max_f32_e32 v34, 0, v34
	v_max_f32_e32 v36, 0, v36
	v_mul_f32_e32 v32, v32, v32
	v_mul_f32_e32 v33, v33, v33
	v_max_f32_e32 v35, 0, v35
	v_mul_f32_e32 v34, v34, v34
	v_max_f32_e32 v24, v24, v24
	v_mul_f32_e32 v36, v36, v36
	v_mul_f32_e32 v35, v35, v35
	v_cvt_pk_bf16_f32 v32, v36, v32
	v_cvt_pk_bf16_f32 v33, v33, v34
	v_cvt_pk_bf16_f32 v34, v40, v37
	v_max_f32_e32 v24, 0, v24
	v_max_f32_e32 v25, v25, v25
	v_max_f32_e32 v26, v26, v26
	v_cvt_pk_bf16_f32 v35, v38, v35
	global_store_dwordx4 v[48:49], v[32:35], off offset:256
	v_max_f32_e32 v28, v28, v28
	v_max_f32_e32 v25, 0, v25
	v_mul_f32_e32 v34, v24, v24
	v_max_f32_e32 v24, v29, v29
	v_max_f32_e32 v26, 0, v26
	s_mov_b64 s[2:3], 0x280000
	v_max_f32_e32 v28, 0, v28
	v_max_f32_e32 v24, 0, v24
	v_mul_f32_e32 v29, v25, v25
	v_max_f32_e32 v25, v30, v30
	v_mul_f32_e32 v30, v26, v26
	v_max_f32_e32 v26, v31, v31
	v_lshl_add_u64 v[32:33], v[138:139], 0, s[2:3]
	v_mul_f32_e32 v28, v28, v28
	v_mul_f32_e32 v24, v24, v24
	v_max_f32_e32 v25, 0, v25
	v_max_f32_e32 v26, 0, v26
	v_max_f32_e32 v27, v27, v27
	s_mov_b32 s2, 0x280000
	v_mul_f32_e32 v25, v25, v25
	v_max_f32_e32 v27, 0, v27
	v_mul_f32_e32 v26, v26, v26
	v_cvt_pk_bf16_f32 v24, v28, v24
	v_add_co_u32_e32 v28, vcc, s2, v138
	v_max_f32_e32 v16, v16, v16
	v_max_f32_e32 v17, v17, v17
	v_max_f32_e32 v18, v18, v18
	v_mul_f32_e32 v27, v27, v27
	v_cvt_pk_bf16_f32 v25, v25, v26
	v_cvt_pk_bf16_f32 v26, v34, v29
	v_addc_co_u32_e32 v29, vcc, 0, v139, vcc
	v_max_f32_e32 v16, 0, v16
	v_max_f32_e32 v17, 0, v17
	v_max_f32_e32 v18, 0, v18
	v_cvt_pk_bf16_f32 v27, v30, v27
	global_store_dwordx4 v[28:29], v[24:27], off
	v_max_f32_e32 v20, v20, v20
	v_max_f32_e32 v19, v19, v19
	v_mul_f32_e32 v24, v16, v16
	v_max_f32_e32 v16, v21, v21
	v_mul_f32_e32 v21, v17, v17
	v_max_f32_e32 v17, v22, v22
	v_mul_f32_e32 v22, v18, v18
	v_max_f32_e32 v18, v23, v23
	v_max_f32_e32 v16, 0, v16
	v_max_f32_e32 v17, 0, v17
	v_max_f32_e32 v18, 0, v18
	v_max_f32_e32 v20, 0, v20
	v_mul_f32_e32 v16, v16, v16
	v_mul_f32_e32 v17, v17, v17
	v_max_f32_e32 v19, 0, v19
	v_mul_f32_e32 v18, v18, v18
	v_max_f32_e32 v8, v8, v8
	v_mul_f32_e32 v20, v20, v20
	v_mul_f32_e32 v19, v19, v19
	v_cvt_pk_bf16_f32 v16, v20, v16
	v_cvt_pk_bf16_f32 v17, v17, v18
	v_cvt_pk_bf16_f32 v18, v24, v21
	v_max_f32_e32 v8, 0, v8
	v_max_f32_e32 v9, v9, v9
	v_max_f32_e32 v10, v10, v10
	v_cvt_pk_bf16_f32 v19, v22, v19
	global_store_dwordx4 v[32:33], v[16:19], off offset:256
	v_max_f32_e32 v12, v12, v12
	v_max_f32_e32 v9, 0, v9
	v_mul_f32_e32 v18, v8, v8
	v_max_f32_e32 v8, v13, v13
	v_max_f32_e32 v10, 0, v10
	s_mov_b64 s[2:3], 0x2c0000
	v_max_f32_e32 v12, 0, v12
	v_max_f32_e32 v8, 0, v8
	v_mul_f32_e32 v13, v9, v9
	v_max_f32_e32 v9, v14, v14
	v_mul_f32_e32 v14, v10, v10
	v_max_f32_e32 v10, v15, v15
	v_lshl_add_u64 v[16:17], v[138:139], 0, s[2:3]
	v_mul_f32_e32 v12, v12, v12
	v_mul_f32_e32 v8, v8, v8
	v_max_f32_e32 v9, 0, v9
	v_max_f32_e32 v10, 0, v10
	v_max_f32_e32 v11, v11, v11
	s_mov_b32 s2, 0x2c0000
	v_mul_f32_e32 v9, v9, v9
	v_max_f32_e32 v11, 0, v11
	v_mul_f32_e32 v10, v10, v10
	v_cvt_pk_bf16_f32 v8, v12, v8
	v_add_co_u32_e32 v12, vcc, s2, v138
	v_max_f32_e32 v0, v0, v0
	v_max_f32_e32 v1, v1, v1
	v_max_f32_e32 v2, v2, v2
	v_mul_f32_e32 v11, v11, v11
	v_cvt_pk_bf16_f32 v9, v9, v10
	v_cvt_pk_bf16_f32 v10, v18, v13
	v_addc_co_u32_e32 v13, vcc, 0, v139, vcc
	v_max_f32_e32 v0, 0, v0
	v_max_f32_e32 v1, 0, v1
	v_max_f32_e32 v2, 0, v2
	v_cvt_pk_bf16_f32 v11, v14, v11
	global_store_dwordx4 v[12:13], v[8:11], off
	v_max_f32_e32 v3, v3, v3
	v_max_f32_e32 v4, v4, v4
	v_mul_f32_e32 v8, v0, v0
	v_max_f32_e32 v0, v5, v5
	v_mul_f32_e32 v5, v1, v1
	v_max_f32_e32 v1, v6, v6
	v_mul_f32_e32 v6, v2, v2
	v_max_f32_e32 v2, v7, v7
	v_max_f32_e32 v0, 0, v0
	v_max_f32_e32 v1, 0, v1
	v_max_f32_e32 v2, 0, v2
	v_max_f32_e32 v3, 0, v3
	v_max_f32_e32 v4, 0, v4
	v_mul_f32_e32 v0, v0, v0
	v_mul_f32_e32 v1, v1, v1
	v_mul_f32_e32 v2, v2, v2
	v_mul_f32_e32 v3, v3, v3
	s_and_b64 vcc, exec, s[0:1]
	s_mov_b32 s67, s14
	s_mov_b32 s38, s28
	s_mov_b64 s[4:5], s[36:37]
	s_mov_b64 s[2:3], s[34:35]
	v_mul_f32_e32 v4, v4, v4
	v_cvt_pk_bf16_f32 v0, v4, v0
	v_cvt_pk_bf16_f32 v1, v1, v2
	v_cvt_pk_bf16_f32 v2, v8, v5
	v_cvt_pk_bf16_f32 v3, v6, v3
	global_store_dwordx4 v[16:17], v[0:3], off offset:256
	s_cbranch_vccz .LBB0_253
	s_waitcnt vmcnt(0)
	v_readlane_b32 s62, v254, 59
	s_cmpk_gt_u32 s41, 0xff
	v_readlane_b32 s55, v254, 57
	v_readlane_b32 s58, v254, 58
	v_readlane_b32 s63, v254, 60
	v_readlane_b32 s59, v255, 1
	s_movk_i32 s66, 0x3000
	v_readlane_b32 s49, v255, 18
	s_cbranch_scc1 .LBB0_260
	s_barrier

.LBB0_329:
	v_add_u32_e32 v140, 0x10000, v249
	ds_read_b128 v[128:131], v140
	ds_read_b128 v[132:135], v140 offset:1024
	ds_read_b128 v[136:139], v140 offset:2048
	ds_read_b128 v[140:143], v140 offset:3072
	ds_read_b128 v[144:147], v250
	ds_read_b128 v[148:151], v250 offset:1024
	ds_read_b128 v[152:155], v250 offset:2048
	ds_read_b128 v[156:159], v250 offset:3072
	ds_read_b128 v[160:163], v250 offset:4096
	ds_read_b128 v[164:167], v250 offset:5120
	ds_read_b128 v[168:171], v250 offset:6144
	ds_read_b128 v[172:175], v250 offset:7168
	v_add_u32_e32 v188, 0x14000, v249
	ds_read_b128 v[176:179], v188
	ds_read_b128 v[180:183], v188 offset:1024
	ds_read_b128 v[184:187], v188 offset:2048
	ds_read_b128 v[188:191], v188 offset:3072
	s_add_u32 s2, s0, 0xfff80080
	s_addc_u32 s3, s1, -1
	s_add_i32 s9, 0, 0x10000
	s_cmp_eq_u32 s40, 28
	s_cselect_b32 s5, s53, s3
	s_cselect_b32 s4, s52, s2
	s_cselect_b32 s3, s67, s37
	s_cselect_b32 s2, s66, s36
	s_add_i32 m0, s51, 0xc000
	s_nop 0
	global_load_lds_dwordx4 v202, s[0:1]
	s_add_i32 m0, s51, 0xe000
	s_nop 0
	global_load_lds_dwordx4 v204, s[0:1]
	s_waitcnt vmcnt(8)
	s_waitcnt lgkmcnt(0)
	s_barrier
	s_setprio 1
	v_mfma_f32_16x16x32_bf16 v[124:127], v[128:131], v[144:147], v[124:127]
	v_mfma_f32_16x16x32_bf16 v[120:123], v[136:139], v[144:147], v[120:123]
	v_mfma_f32_16x16x32_bf16 v[108:111], v[128:131], v[152:155], v[108:111]
	v_mfma_f32_16x16x32_bf16 v[104:107], v[136:139], v[152:155], v[104:107]
	v_mfma_f32_16x16x32_bf16 v[92:95], v[128:131], v[160:163], v[92:95]
	v_mfma_f32_16x16x32_bf16 v[88:91], v[136:139], v[160:163], v[88:91]
	v_mfma_f32_16x16x32_bf16 v[76:79], v[128:131], v[168:171], v[76:79]
	v_mfma_f32_16x16x32_bf16 v[72:75], v[136:139], v[168:171], v[72:75]
	v_mfma_f32_16x16x32_bf16 v[124:127], v[132:135], v[148:151], v[124:127]
	v_mfma_f32_16x16x32_bf16 v[120:123], v[140:143], v[148:151], v[120:123]
	v_mfma_f32_16x16x32_bf16 v[108:111], v[132:135], v[156:159], v[108:111]
	v_mfma_f32_16x16x32_bf16 v[104:107], v[140:143], v[156:159], v[104:107]
	v_mfma_f32_16x16x32_bf16 v[92:95], v[132:135], v[164:167], v[92:95]
	v_mfma_f32_16x16x32_bf16 v[88:91], v[140:143], v[164:167], v[88:91]
	v_mfma_f32_16x16x32_bf16 v[76:79], v[132:135], v[172:175], v[76:79]
	v_mfma_f32_16x16x32_bf16 v[72:75], v[140:143], v[172:175], v[72:75]
	v_mfma_f32_16x16x32_bf16 v[116:119], v[176:179], v[144:147], v[116:119]
	v_mfma_f32_16x16x32_bf16 v[112:115], v[184:187], v[144:147], v[112:115]
	v_mfma_f32_16x16x32_bf16 v[100:103], v[176:179], v[152:155], v[100:103]
	v_mfma_f32_16x16x32_bf16 v[96:99], v[184:187], v[152:155], v[96:99]
	v_mfma_f32_16x16x32_bf16 v[84:87], v[176:179], v[160:163], v[84:87]
	v_mfma_f32_16x16x32_bf16 v[80:83], v[184:187], v[160:163], v[80:83]
	v_mfma_f32_16x16x32_bf16 v[68:71], v[176:179], v[168:171], v[68:71]
	v_mfma_f32_16x16x32_bf16 v[64:67], v[184:187], v[168:171], v[64:67]
	v_mfma_f32_16x16x32_bf16 v[116:119], v[180:183], v[148:151], v[116:119]
	v_mfma_f32_16x16x32_bf16 v[112:115], v[188:191], v[148:151], v[112:115]
	v_mfma_f32_16x16x32_bf16 v[100:103], v[180:183], v[156:159], v[100:103]
	v_mfma_f32_16x16x32_bf16 v[96:99], v[188:191], v[156:159], v[96:99]
	v_mfma_f32_16x16x32_bf16 v[84:87], v[180:183], v[164:167], v[84:87]
	v_mfma_f32_16x16x32_bf16 v[80:83], v[188:191], v[164:167], v[80:83]
	v_mfma_f32_16x16x32_bf16 v[68:71], v[180:183], v[172:175], v[68:71]
	v_mfma_f32_16x16x32_bf16 v[64:67], v[188:191], v[172:175], v[64:67]
	s_setprio 0
	s_barrier
	ds_read_b128 v[144:147], v250 offset:16384
	ds_read_b128 v[148:151], v250 offset:17408
	ds_read_b128 v[152:155], v250 offset:18432
	ds_read_b128 v[156:159], v250 offset:19456
	ds_read_b128 v[160:163], v250 offset:20480
	ds_read_b128 v[164:167], v250 offset:21504
	ds_read_b128 v[168:171], v250 offset:22528
	ds_read_b128 v[172:175], v250 offset:23552
	s_add_i32 s41, 0, 0x14000
	s_add_i32 s9, s9, s50
	s_add_u32 vcc_lo, s2, 0x80
	s_addc_u32 vcc_hi, s3, 0
	s_mov_b32 m0, s9
	s_nop 0
	global_load_lds_dwordx4 v196, s[2:3]
	s_add_i32 m0, s9, 0x2000
	s_nop 0
	global_load_lds_dwordx4 v200, s[2:3]
	s_mov_b32 m0, s51
	s_add_u32 s98, s4, 0x80
	s_addc_u32 s99, s5, 0
	global_load_lds_dwordx4 v194, s[4:5]
	s_mov_b32 m0, s62
	s_nop 0
	global_load_lds_dwordx4 v198, s[4:5]
	s_add_u32 s46, s2, 0x80000
	s_addc_u32 s47, s3, 0
	s_add_i32 s9, s41, s50
	s_mov_b32 m0, s9
	s_nop 0
	global_load_lds_dwordx4 v196, s[46:47]
	s_add_i32 m0, s9, 0x2000
	s_nop 0
	global_load_lds_dwordx4 v200, s[46:47]
	s_waitcnt vmcnt(8)
	s_waitcnt lgkmcnt(0)
	s_barrier
	s_setprio 1
	v_mfma_f32_16x16x32_bf16 v[60:63], v[128:131], v[144:147], v[60:63]
	v_mfma_f32_16x16x32_bf16 v[56:59], v[136:139], v[144:147], v[56:59]
	v_mfma_f32_16x16x32_bf16 v[44:47], v[128:131], v[152:155], v[44:47]
	v_mfma_f32_16x16x32_bf16 v[40:43], v[136:139], v[152:155], v[40:43]
	v_mfma_f32_16x16x32_bf16 v[28:31], v[128:131], v[160:163], v[28:31]
	v_mfma_f32_16x16x32_bf16 v[24:27], v[136:139], v[160:163], v[24:27]
	v_mfma_f32_16x16x32_bf16 v[12:15], v[128:131], v[168:171], v[12:15]
	v_mfma_f32_16x16x32_bf16 v[8:11], v[136:139], v[168:171], v[8:11]
	v_mfma_f32_16x16x32_bf16 v[60:63], v[132:135], v[148:151], v[60:63]
	v_mfma_f32_16x16x32_bf16 v[56:59], v[140:143], v[148:151], v[56:59]
	v_mfma_f32_16x16x32_bf16 v[44:47], v[132:135], v[156:159], v[44:47]
	v_mfma_f32_16x16x32_bf16 v[40:43], v[140:143], v[156:159], v[40:43]
	v_mfma_f32_16x16x32_bf16 v[28:31], v[132:135], v[164:167], v[28:31]
	v_mfma_f32_16x16x32_bf16 v[24:27], v[140:143], v[164:167], v[24:27]
	v_mfma_f32_16x16x32_bf16 v[12:15], v[132:135], v[172:175], v[12:15]
	v_mfma_f32_16x16x32_bf16 v[8:11], v[140:143], v[172:175], v[8:11]
	v_mfma_f32_16x16x32_bf16 v[52:55], v[176:179], v[144:147], v[52:55]
	v_mfma_f32_16x16x32_bf16 v[48:51], v[184:187], v[144:147], v[48:51]
	v_mfma_f32_16x16x32_bf16 v[36:39], v[176:179], v[152:155], v[36:39]
	v_mfma_f32_16x16x32_bf16 v[32:35], v[184:187], v[152:155], v[32:35]
	v_mfma_f32_16x16x32_bf16 v[20:23], v[176:179], v[160:163], v[20:23]
	v_mfma_f32_16x16x32_bf16 v[16:19], v[184:187], v[160:163], v[16:19]
	v_mfma_f32_16x16x32_bf16 v[4:7], v[176:179], v[168:171], v[4:7]
	v_mfma_f32_16x16x32_bf16 v[0:3], v[184:187], v[168:171], v[0:3]
	v_mfma_f32_16x16x32_bf16 v[52:55], v[180:183], v[148:151], v[52:55]
	v_mfma_f32_16x16x32_bf16 v[48:51], v[188:191], v[148:151], v[48:51]
	v_mfma_f32_16x16x32_bf16 v[36:39], v[180:183], v[156:159], v[36:39]
	v_mfma_f32_16x16x32_bf16 v[32:35], v[188:191], v[156:159], v[32:35]
	v_mfma_f32_16x16x32_bf16 v[20:23], v[180:183], v[164:167], v[20:23]
	v_mfma_f32_16x16x32_bf16 v[16:19], v[188:191], v[164:167], v[16:19]
	v_mfma_f32_16x16x32_bf16 v[4:7], v[180:183], v[172:175], v[4:7]
	v_mfma_f32_16x16x32_bf16 v[0:3], v[188:191], v[172:175], v[0:3]
	s_setprio 0
	s_barrier
	v_add_u32_e32 v140, 0x18000, v249
	ds_read_b128 v[128:131], v140
	ds_read_b128 v[132:135], v140 offset:1024
	ds_read_b128 v[136:139], v140 offset:2048
	ds_read_b128 v[140:143], v140 offset:3072
	ds_read_b128 v[144:147], v250 offset:32768
	ds_read_b128 v[148:151], v250 offset:33792
	ds_read_b128 v[152:155], v250 offset:34816
	ds_read_b128 v[156:159], v250 offset:35840
	ds_read_b128 v[160:163], v250 offset:36864
	ds_read_b128 v[164:167], v250 offset:37888
	ds_read_b128 v[168:171], v250 offset:38912
	ds_read_b128 v[172:175], v250 offset:39936
	v_add_u32_e32 v188, 0x1c000, v249
	ds_read_b128 v[176:179], v188
	ds_read_b128 v[180:183], v188 offset:1024
	ds_read_b128 v[184:187], v188 offset:2048
	ds_read_b128 v[188:191], v188 offset:3072
	s_add_i32 s9, 0, 0x18000
	s_add_u32 s4, s4, 0x80000
	s_addc_u32 s5, s5, 0
	s_mov_b32 m0, s63
	s_nop 0
	global_load_lds_dwordx4 v194, s[4:5]
	s_mov_b32 m0, s69
	s_nop 0
	global_load_lds_dwordx4 v198, s[4:5]
	s_waitcnt vmcnt(8)
	s_waitcnt lgkmcnt(0)
	s_barrier
	s_setprio 1
	v_mfma_f32_16x16x32_bf16 v[124:127], v[128:131], v[144:147], v[124:127]
	v_mfma_f32_16x16x32_bf16 v[120:123], v[136:139], v[144:147], v[120:123]
	v_mfma_f32_16x16x32_bf16 v[108:111], v[128:131], v[152:155], v[108:111]
	v_mfma_f32_16x16x32_bf16 v[104:107], v[136:139], v[152:155], v[104:107]
	v_mfma_f32_16x16x32_bf16 v[92:95], v[128:131], v[160:163], v[92:95]
	v_mfma_f32_16x16x32_bf16 v[88:91], v[136:139], v[160:163], v[88:91]
	v_mfma_f32_16x16x32_bf16 v[76:79], v[128:131], v[168:171], v[76:79]
	v_mfma_f32_16x16x32_bf16 v[72:75], v[136:139], v[168:171], v[72:75]
	v_mfma_f32_16x16x32_bf16 v[124:127], v[132:135], v[148:151], v[124:127]
	v_mfma_f32_16x16x32_bf16 v[120:123], v[140:143], v[148:151], v[120:123]
	v_mfma_f32_16x16x32_bf16 v[108:111], v[132:135], v[156:159], v[108:111]
	v_mfma_f32_16x16x32_bf16 v[104:107], v[140:143], v[156:159], v[104:107]
	v_mfma_f32_16x16x32_bf16 v[92:95], v[132:135], v[164:167], v[92:95]
	v_mfma_f32_16x16x32_bf16 v[88:91], v[140:143], v[164:167], v[88:91]
	v_mfma_f32_16x16x32_bf16 v[76:79], v[132:135], v[172:175], v[76:79]
	v_mfma_f32_16x16x32_bf16 v[72:75], v[140:143], v[172:175], v[72:75]
	v_mfma_f32_16x16x32_bf16 v[116:119], v[176:179], v[144:147], v[116:119]
	v_mfma_f32_16x16x32_bf16 v[112:115], v[184:187], v[144:147], v[112:115]
	v_mfma_f32_16x16x32_bf16 v[100:103], v[176:179], v[152:155], v[100:103]
	v_mfma_f32_16x16x32_bf16 v[96:99], v[184:187], v[152:155], v[96:99]
	v_mfma_f32_16x16x32_bf16 v[84:87], v[176:179], v[160:163], v[84:87]
	v_mfma_f32_16x16x32_bf16 v[80:83], v[184:187], v[160:163], v[80:83]
	v_mfma_f32_16x16x32_bf16 v[68:71], v[176:179], v[168:171], v[68:71]
	v_mfma_f32_16x16x32_bf16 v[64:67], v[184:187], v[168:171], v[64:67]
	v_mfma_f32_16x16x32_bf16 v[116:119], v[180:183], v[148:151], v[116:119]
	v_mfma_f32_16x16x32_bf16 v[112:115], v[188:191], v[148:151], v[112:115]
	v_mfma_f32_16x16x32_bf16 v[100:103], v[180:183], v[156:159], v[100:103]
	v_mfma_f32_16x16x32_bf16 v[96:99], v[188:191], v[156:159], v[96:99]
	v_mfma_f32_16x16x32_bf16 v[84:87], v[180:183], v[164:167], v[84:87]
	v_mfma_f32_16x16x32_bf16 v[80:83], v[188:191], v[164:167], v[80:83]
	v_mfma_f32_16x16x32_bf16 v[68:71], v[180:183], v[172:175], v[68:71]
	v_mfma_f32_16x16x32_bf16 v[64:67], v[188:191], v[172:175], v[64:67]
	s_setprio 0
	s_barrier
	ds_read_b128 v[144:147], v250 offset:49152
	ds_read_b128 v[148:151], v250 offset:50176
	ds_read_b128 v[152:155], v250 offset:51200
	ds_read_b128 v[156:159], v250 offset:52224
	ds_read_b128 v[160:163], v250 offset:53248
	ds_read_b128 v[164:167], v250 offset:54272
	ds_read_b128 v[168:171], v250 offset:55296
	ds_read_b128 v[172:175], v250 offset:56320
	s_add_i32 s4, 0, 0x1c000
	s_add_i32 s5, s9, s50
	s_mov_b32 m0, s5
	s_nop 0
	global_load_lds_dwordx4 v196, vcc
	s_add_i32 m0, s5, 0x2000
	s_nop 0
	global_load_lds_dwordx4 v200, vcc
	s_mov_b32 m0, s71
	s_nop 0
	global_load_lds_dwordx4 v194, s[98:99]
	s_mov_b32 m0, s75
	s_nop 0
	global_load_lds_dwordx4 v198, s[98:99]
	s_add_u32 s2, s2, 0x80080
	s_addc_u32 s3, s3, 0
	s_add_i32 s4, s4, s50
	s_mov_b32 m0, s4
	s_nop 0
	global_load_lds_dwordx4 v196, s[2:3]
	s_add_i32 m0, s4, 0x2000
	s_nop 0
	global_load_lds_dwordx4 v200, s[2:3]
	s_waitcnt vmcnt(8)
	s_waitcnt lgkmcnt(0)
	s_barrier
	s_setprio 1
	v_mfma_f32_16x16x32_bf16 v[60:63], v[128:131], v[144:147], v[60:63]
	v_mfma_f32_16x16x32_bf16 v[56:59], v[136:139], v[144:147], v[56:59]
	v_mfma_f32_16x16x32_bf16 v[44:47], v[128:131], v[152:155], v[44:47]
	v_mfma_f32_16x16x32_bf16 v[40:43], v[136:139], v[152:155], v[40:43]
	v_mfma_f32_16x16x32_bf16 v[28:31], v[128:131], v[160:163], v[28:31]
	v_mfma_f32_16x16x32_bf16 v[24:27], v[136:139], v[160:163], v[24:27]
	v_mfma_f32_16x16x32_bf16 v[12:15], v[128:131], v[168:171], v[12:15]
	v_mfma_f32_16x16x32_bf16 v[8:11], v[136:139], v[168:171], v[8:11]
	v_mfma_f32_16x16x32_bf16 v[60:63], v[132:135], v[148:151], v[60:63]
	v_mfma_f32_16x16x32_bf16 v[56:59], v[140:143], v[148:151], v[56:59]
	v_mfma_f32_16x16x32_bf16 v[44:47], v[132:135], v[156:159], v[44:47]
	v_mfma_f32_16x16x32_bf16 v[40:43], v[140:143], v[156:159], v[40:43]
	v_mfma_f32_16x16x32_bf16 v[28:31], v[132:135], v[164:167], v[28:31]
	v_mfma_f32_16x16x32_bf16 v[24:27], v[140:143], v[164:167], v[24:27]
	v_mfma_f32_16x16x32_bf16 v[12:15], v[132:135], v[172:175], v[12:15]
	v_mfma_f32_16x16x32_bf16 v[8:11], v[140:143], v[172:175], v[8:11]
	v_mfma_f32_16x16x32_bf16 v[52:55], v[176:179], v[144:147], v[52:55]
	v_mfma_f32_16x16x32_bf16 v[48:51], v[184:187], v[144:147], v[48:51]
	v_mfma_f32_16x16x32_bf16 v[36:39], v[176:179], v[152:155], v[36:39]
	v_mfma_f32_16x16x32_bf16 v[32:35], v[184:187], v[152:155], v[32:35]
	v_mfma_f32_16x16x32_bf16 v[20:23], v[176:179], v[160:163], v[20:23]
	v_mfma_f32_16x16x32_bf16 v[16:19], v[184:187], v[160:163], v[16:19]
	v_mfma_f32_16x16x32_bf16 v[4:7], v[176:179], v[168:171], v[4:7]
	v_mfma_f32_16x16x32_bf16 v[0:3], v[184:187], v[168:171], v[0:3]
	v_mfma_f32_16x16x32_bf16 v[52:55], v[180:183], v[148:151], v[52:55]
	v_mfma_f32_16x16x32_bf16 v[48:51], v[188:191], v[148:151], v[48:51]
	v_mfma_f32_16x16x32_bf16 v[36:39], v[180:183], v[156:159], v[36:39]
	v_mfma_f32_16x16x32_bf16 v[32:35], v[188:191], v[156:159], v[32:35]
	v_mfma_f32_16x16x32_bf16 v[20:23], v[180:183], v[164:167], v[20:23]
	v_mfma_f32_16x16x32_bf16 v[16:19], v[188:191], v[164:167], v[16:19]
	v_mfma_f32_16x16x32_bf16 v[4:7], v[180:183], v[172:175], v[4:7]
	v_mfma_f32_16x16x32_bf16 v[0:3], v[188:191], v[172:175], v[0:3]
	s_setprio 0
	s_add_i32 s40, s40, 2
	s_add_u32 s0, s0, 0x100
	s_addc_u32 s1, s1, 0
	s_add_u32 s36, s36, 0x100
	s_addc_u32 s37, s37, 0
	s_cmp_gt_u32 s40, 29
	s_barrier
	s_cbranch_scc0 .LBB0_329
	v_mov_b32 v128, v248
	s_cmp_gt_u32 s38, 1
	v_and_b32_e32 v246, 15, v128
	v_ashrrev_i32_e32 v247, 4, v128
	s_mov_b64 s[0:1], -1
	s_cbranch_scc0 .LBB0_413
	s_and_b32 s4, s39, 3
	s_cmp_lg_u32 s38, 2
	s_cbranch_scc0 .LBB0_400
	s_lshl_b32 s40, s49, 8
	v_or_b32_e32 v128, s78, v246
	v_add_u32_e32 v134, s40, v128
	v_min_i32_e32 v130, 0x2000, v134
	v_lshlrev_b32_e32 v130, 8, v130
	v_add_lshl_u32 v206, v247, s85, 2
	v_readlane_b32 s0, v251, 61
	v_and_b32_e32 v192, 0x7cf00, v130
	v_or_b32_e32 v130, 16, v134
	v_ashrrev_i32_e32 v207, 31, v206
	v_readlane_b32 s1, v251, 62
	v_min_i32_e32 v130, 0x2000, v130
	v_or_b32_e32 v132, 32, v134
	v_lshl_add_u64 v[128:129], v[206:207], 2, s[0:1]
	v_lshlrev_b32_e32 v130, 8, v130
	v_min_i32_e32 v132, 0x2000, v132
	v_lshl_add_u64 v[210:211], v[128:129], 0, v[192:193]
	v_and_b32_e32 v192, 0x7ff00, v130
	v_lshlrev_b32_e32 v132, 8, v132
	v_lshl_add_u64 v[130:131], v[128:129], 0, v[192:193]
	v_and_b32_e32 v192, 0x7ff00, v132
	global_load_dwordx4 v[188:191], v[210:211], off offset:128
	global_load_dwordx4 v[176:179], v[130:131], off
	v_lshl_add_u64 v[132:133], v[128:129], 0, v[192:193]
	global_load_dwordx4 v[180:183], v[130:131], off offset:128
	global_load_dwordx4 v[168:171], v[132:133], off
	v_or_b32_e32 v130, 48, v134
	v_min_i32_e32 v130, 0x2000, v130
	v_lshlrev_b32_e32 v130, 8, v130
	v_and_b32_e32 v192, 0x7ff00, v130
	v_lshl_add_u64 v[130:131], v[128:129], 0, v[192:193]
	global_load_dwordx4 v[172:175], v[132:133], off offset:128
	global_load_dwordx4 v[160:163], v[130:131], off
	v_add_u32_e32 v132, 0x80, v134
	v_min_i32_e32 v132, 0x2000, v132
	v_lshlrev_b32_e32 v132, 8, v132
	v_and_b32_e32 v192, 0x7ff00, v132
	v_lshl_add_u64 v[132:133], v[128:129], 0, v[192:193]
	global_load_dwordx4 v[164:167], v[130:131], off offset:128
	global_load_dwordx4 v[152:155], v[132:133], off
	v_add_u32_e32 v130, 0x90, v134
	v_min_i32_e32 v130, 0x2000, v130
	v_lshlrev_b32_e32 v130, 8, v130
	v_and_b32_e32 v192, 0x7ff00, v130
	v_lshl_add_u64 v[130:131], v[128:129], 0, v[192:193]
	global_load_dwordx4 v[156:159], v[132:133], off offset:128
	global_load_dwordx4 v[144:147], v[130:131], off
	v_add_u32_e32 v132, 0xa0, v134
	v_min_i32_e32 v132, 0x2000, v132
	v_lshlrev_b32_e32 v132, 8, v132
	v_and_b32_e32 v192, 0x7ff00, v132
	v_lshl_add_u64 v[132:133], v[128:129], 0, v[192:193]
	global_load_dwordx4 v[148:151], v[130:131], off offset:128
	global_load_dwordx4 v[136:139], v[132:133], off
	v_add_u32_e32 v130, 0xb0, v134
	v_min_i32_e32 v130, 0x2000, v130
	v_lshlrev_b32_e32 v130, 8, v130
	v_and_b32_e32 v192, 0x7ff00, v130
	v_lshl_add_u64 v[128:129], v[128:129], 0, v[192:193]
	global_load_dwordx4 v[140:143], v[132:133], off offset:128
	s_nop 0
	global_load_dwordx4 v[132:135], v[128:129], off
	s_nop 0
	global_load_dwordx4 v[128:131], v[128:129], off offset:128
	s_add_i32 s2, s40, s78
	v_or_b32_e32 v208, s2, v246
	v_mov_b32_e32 v184, 1.0
	v_cmp_gt_i32_e32 vcc, s33, v208
	v_mov_b32_e32 v185, v184
	v_mov_b32_e32 v186, v184
	v_mov_b32_e32 v187, v184
	s_and_saveexec_b64 s[0:1], vcc
	s_cbranch_execz .LBB0_334
	global_load_dwordx4 v[184:187], v[210:211], off
